# hand-written cp_load/cp_store address math (no integer divisions) in P1 epilogue + relaxed vmcnt waits in P1/S4 epilogues
# speedup vs baseline: 1.0069x; 1.0069x over previous
.LBB0_371:
	s_cmpk_lt_i32 s1, 0x80
	s_cselect_b64 s[2:3], -1, 0
	s_bitcmp1_b32 s1, 3
	s_cselect_b64 s[6:7], -1, 0
	s_and_b64 s[2:3], s[2:3], s[6:7]
	s_cmp_gt_i32 s72, 10
	s_cselect_b64 s[6:7], -1, 0
	s_mul_i32 s0, s1, 25
	s_and_b64 s[2:3], s[6:7], s[2:3]
	s_add_i32 s0, s0, s72
	s_and_b64 s[2:3], s[2:3], exec
	v_mov_b32_e32 v145, 0
	s_cselect_b32 s53, 0x1550, s0
	s_cmp_lt_i32 s72, 9
	v_mov_b32_e32 v144, v145
	v_mov_b32_e32 v143, v145
	v_mov_b32_e32 v142, v145
	v_mov_b32_e32 v141, v145
	v_mov_b32_e32 v140, v145
	v_mov_b32_e32 v139, v145
	v_mov_b32_e32 v138, v145
	v_mov_b32_e32 v137, v145
	v_mov_b32_e32 v136, v145
	v_mov_b32_e32 v135, v145
	v_mov_b32_e32 v134, v145
	v_mov_b32_e32 v117, v145
	v_mov_b32_e32 v116, v145
	v_mov_b32_e32 v115, v145
	v_mov_b32_e32 v114, v145
	s_cbranch_scc1 .LBB0_391
	v_mov_b32_e32 v145, 0
	s_cmpk_gt_i32 s53, 0x154f
	v_mov_b32_e32 v144, v145
	v_mov_b32_e32 v143, v145
	v_mov_b32_e32 v142, v145
	v_mov_b32_e32 v141, v145
	v_mov_b32_e32 v140, v145
	v_mov_b32_e32 v139, v145
	v_mov_b32_e32 v138, v145
	v_mov_b32_e32 v137, v145
	v_mov_b32_e32 v136, v145
	v_mov_b32_e32 v135, v145
	v_mov_b32_e32 v134, v145
	v_mov_b32_e32 v117, v145
	v_mov_b32_e32 v116, v145
	v_mov_b32_e32 v115, v145
	v_mov_b32_e32 v114, v145
	s_cbranch_scc1 .LBB0_390
	s_cmpk_lt_u32 s53, 0xf8
	s_cbranch_scc0 .Lcpl1_a
	s_mov_b32 s2, s53
	s_mov_b32 s3, 0x8421085
	s_movk_i32 s6, 0x3e00
	s_movk_i32 s7, 0x200
	s_mov_b64 s[8:9], s[16:17]
	s_add_u32 s100, s28, 0x8280000
	s_addc_u32 s101, s29, 0
	s_branch .Lcpl1_go
.Lcpl1_a:
	s_cmpk_lt_u32 s53, 0x4f0
	s_cbranch_scc0 .Lcpl1_b
	s_add_i32 s2, s53, 0xffffff08
	s_mov_b32 s3, 0x2040811
	s_mov_b32 s6, 0xfe00
	s_movk_i32 s7, 0x200
	s_mov_b64 s[8:9], s[18:19]
	s_add_u32 s100, s28, 0x9280000
	s_addc_u32 s101, s29, 0
	s_branch .Lcpl1_go
.Lcpl1_b:
	s_cmpk_lt_u32 s53, 0x14e8
	s_cbranch_scc0 .Lcpl1_c
	s_add_i32 s2, s53, 0xfffffb10
	s_mov_b32 s3, 0x804021
	s_mov_b32 s6, 0x3fe00
	s_movk_i32 s7, 0x200
	s_mov_b64 s[8:9], s[20:21]
	s_add_u32 s100, s28, 0xd280000
	s_addc_u32 s101, s29, 0
	s_branch .Lcpl1_go
.Lcpl1_c:
	s_add_i32 s2, s53, 0xffffeb18
	s_mov_b32 s3, 0x13b13b14
	s_movk_i32 s6, 0x1a00
	s_movk_i32 s7, 0x400
	s_mov_b64 s[8:9], s[22:23]
	s_mov_b64 s[100:101], s[48:49]
.Lcpl1_go:
	s_lshl_b32 s0, s2, 2
	s_mul_hi_u32 s0, s0, s3
	s_lshl_b32 s2, s2, 11
	s_mul_i32 s10, s0, s6
	s_sub_u32 s10, s2, s10
	s_mul_i32 s11, s0, s7
	s_add_u32 s11, s2, s11
	v_add_u32_e32 v114, s10, v192
	v_add_u32_e32 v134, s10, v193
	v_add_u32_e32 v138, s10, v194
	v_add_u32_e32 v142, s10, v195
	v_cmp_le_u32_e64 s[12:13], s6, v114
	v_cmp_le_u32_e64 s[24:25], s6, v134
	v_cmp_le_u32_e64 s[26:27], s6, v138
	v_cmp_le_u32_e64 vcc, s6, v142
	v_add_u32_e32 v114, s11, v192
	v_add_u32_e32 v134, s11, v193
	v_add_u32_e32 v138, s11, v194
	v_add_u32_e32 v142, s11, v195
	v_mov_b32_e32 v116, s7
	v_cndmask_b32_e64 v115, 0, v116, s[12:13]
	v_cndmask_b32_e64 v135, 0, v116, s[24:25]
	v_cndmask_b32_e64 v139, 0, v116, s[26:27]
	v_cndmask_b32_e64 v143, 0, v116, vcc
	v_add_u32_e32 v114, v114, v115
	v_add_u32_e32 v134, v134, v135
	v_add_u32_e32 v138, v138, v139
	v_add_u32_e32 v142, v142, v143
	v_mov_b32_e32 v115, 0
	v_mov_b32_e32 v135, 0
	v_mov_b32_e32 v139, 0
	v_mov_b32_e32 v143, 0
	v_lshl_add_u64 v[248:249], v[114:115], 4, s[100:101]
	v_lshl_add_u64 v[250:251], v[134:135], 4, s[100:101]
	v_lshl_add_u64 v[252:253], v[138:139], 4, s[100:101]
	v_lshl_add_u64 v[254:255], v[142:143], 4, s[100:101]
	v_add_u32_e32 v114, s7, v114
	v_add_u32_e32 v134, s7, v134
	v_add_u32_e32 v138, s7, v138
	v_add_u32_e32 v142, s7, v142
	v_lshl_add_u64 v[114:115], v[114:115], 4, s[8:9]
	v_lshl_add_u64 v[134:135], v[134:135], 4, s[8:9]
	v_lshl_add_u64 v[138:139], v[138:139], 4, s[8:9]
	v_lshl_add_u64 v[142:143], v[142:143], 4, s[8:9]
	global_load_dwordx4 v[114:117], v[114:115], off nt
	global_load_dwordx4 v[134:137], v[134:135], off nt
	global_load_dwordx4 v[138:141], v[138:139], off nt
	global_load_dwordx4 v[142:145], v[142:143], off nt

.LBB0_394:
	v_mul_f32_e32 v146, 0xbfb8aa3b, v122
	v_mul_f32_e32 v147, 0xbfb8aa3b, v118
	v_mul_f32_e32 v148, 0xbfb8aa3b, v123
	v_mul_f32_e32 v149, 0xbfb8aa3b, v119
	v_mul_f32_e32 v150, 0xbfb8aa3b, v124
	v_mul_f32_e32 v151, 0xbfb8aa3b, v120
	v_mul_f32_e32 v155, 0xbfb8aa3b, v125
	v_mul_f32_e32 v156, 0xbfb8aa3b, v121
	v_mul_f32_e32 v157, 0xbfb8aa3b, v102
	v_mul_f32_e32 v158, 0xbfb8aa3b, v98
	v_mul_f32_e32 v159, 0xbfb8aa3b, v103
	v_mul_f32_e32 v160, 0xbfb8aa3b, v99
	v_mul_f32_e32 v161, 0xbfb8aa3b, v104
	v_mul_f32_e32 v170, 0xbfb8aa3b, v100
	v_mul_f32_e32 v185, 0xbfb8aa3b, v105
	v_mul_f32_e32 v186, 0xbfb8aa3b, v101
	v_mul_f32_e32 v187, 0xbfb8aa3b, v86
	v_mul_f32_e32 v188, 0xbfb8aa3b, v82
	v_mul_f32_e32 v189, 0xbfb8aa3b, v87
	v_mul_f32_e32 v191, 0xbfb8aa3b, v83
	v_mul_f32_e32 v205, 0xbfb8aa3b, v88
	v_mul_f32_e32 v206, 0xbfb8aa3b, v84
	v_mul_f32_e32 v219, 0xbfb8aa3b, v89
	v_mul_f32_e32 v220, 0xbfb8aa3b, v85
	v_mul_f32_e32 v221, 0xbfb8aa3b, v70
	v_mul_f32_e32 v222, 0xbfb8aa3b, v66
	v_mul_f32_e32 v223, 0xbfb8aa3b, v71
	v_mul_f32_e32 v224, 0xbfb8aa3b, v67
	v_mul_f32_e32 v225, 0xbfb8aa3b, v72
	v_mul_f32_e32 v226, 0xbfb8aa3b, v68
	v_mul_f32_e32 v227, 0xbfb8aa3b, v73
	v_mul_f32_e32 v228, 0xbfb8aa3b, v69
	v_exp_f32_e32 v217, v146
	v_exp_f32_e32 v152, v147
	v_exp_f32_e32 v218, v148
	v_exp_f32_e32 v153, v149
	v_exp_f32_e32 v154, v150
	v_exp_f32_e32 v150, v151
	v_exp_f32_e32 v155, v155
	v_exp_f32_e32 v151, v156
	v_exp_f32_e32 v215, v157
	v_exp_f32_e32 v211, v158
	v_exp_f32_e32 v216, v159
	v_exp_f32_e32 v212, v160
	v_exp_f32_e32 v213, v161
	v_exp_f32_e32 v209, v170
	v_exp_f32_e32 v214, v185
	v_exp_f32_e32 v210, v186
	v_exp_f32_e32 v207, v187
	v_exp_f32_e32 v190, v188
	v_exp_f32_e32 v208, v189
	v_exp_f32_e32 v191, v191
	v_exp_f32_e32 v205, v205
	v_exp_f32_e32 v156, v206
	v_exp_f32_e32 v206, v219
	v_exp_f32_e32 v157, v220
	v_exp_f32_e32 v188, v221
	v_exp_f32_e32 v160, v222
	v_exp_f32_e32 v189, v223
	v_exp_f32_e32 v161, v224
	v_exp_f32_e32 v186, v225
	v_exp_f32_e32 v158, v226
	v_exp_f32_e32 v187, v227
	v_exp_f32_e32 v159, v228
	s_cmp_gt_u32 s72, 16
	v_ashrrev_i32_e32 v185, 31, v184
	s_cbranch_scc0 .LBB0_414
	s_sub_i32 s2, s72, 17
	s_cmp_lt_u32 s2, 4
	s_mov_b32 s0, 0xb600000
	s_cselect_b32 s0, s0, 0xb600400
	v_readlane_b32 s6, v246, 2
	v_readlane_b32 s7, v246, 3
	s_add_u32 s0, s6, s0
	s_addc_u32 s1, s7, 0
	s_lshl_b32 s2, s2, 8
	s_and_b32 s2, s2, 0x300
	v_or_b32_e32 v170, s2, v175
	v_lshl_add_u64 v[148:149], s[0:1], 0, v[170:171]
	v_mul_f32_e32 v170, 0xbfb8aa3b, v130
	v_exp_f32_e32 v170, v170
	v_mul_f32_e32 v220, 0xbfb8aa3b, v131
	v_exp_f32_e32 v220, v220
	v_mul_f32_e32 v222, 0xbfb8aa3b, v132
	v_exp_f32_e32 v222, v222
	v_add_f32_e32 v170, 1.0, v170
	v_mul_f32_e32 v224, 0xbfb8aa3b, v133
	v_rcp_f32_e32 v170, v170
	v_add_f32_e32 v220, 1.0, v220
	v_exp_f32_e32 v224, v224
	v_mul_f32_e32 v219, 0xbfb8aa3b, v126
	v_rcp_f32_e32 v220, v220
	v_exp_f32_e32 v219, v219
	v_mul_f32_e32 v221, 0xbfb8aa3b, v127
	v_add_f32_e32 v222, 1.0, v222
	v_exp_f32_e32 v221, v221
	v_rcp_f32_e32 v222, v222
	v_mul_f32_e32 v223, 0xbfb8aa3b, v128
	v_add_f32_e32 v224, 1.0, v224
	v_mul_f32_e32 v170, 0x437f0000, v170
	v_exp_f32_e32 v223, v223
	v_rcp_f32_e32 v224, v224
	v_rndne_f32_e32 v170, v170
	v_mul_f32_e32 v220, 0x437f0000, v220
	v_add_f32_e32 v219, 1.0, v219
	v_mul_f32_e32 v225, 0xbfb8aa3b, v129
	v_cvt_pk_u8_f32 v170, v170, 0, 0
	v_rndne_f32_e32 v220, v220
	v_rcp_f32_e32 v219, v219
	v_add_f32_e32 v221, 1.0, v221
	v_exp_f32_e32 v225, v225
	v_cvt_pk_u8_f32 v170, v220, 1, v170
	v_mul_f32_e32 v220, 0x437f0000, v222
	v_rcp_f32_e32 v221, v221
	v_rndne_f32_e32 v220, v220
	v_add_f32_e32 v223, 1.0, v223
	v_cvt_pk_u8_f32 v170, v220, 2, v170
	v_mul_f32_e32 v220, 0x437f0000, v224
	v_rcp_f32_e32 v223, v223
	v_rndne_f32_e32 v220, v220
	v_add_f32_e32 v225, 1.0, v225
	v_cvt_pk_u8_f32 v220, v220, 3, v170
	v_mul_f32_e32 v170, 0x437f0000, v219
	v_rcp_f32_e32 v225, v225
	v_rndne_f32_e32 v170, v170
	v_mul_f32_e32 v219, 0x437f0000, v221
	v_cvt_pk_u8_f32 v170, v170, 0, 0
	v_rndne_f32_e32 v219, v219
	v_cvt_pk_u8_f32 v170, v219, 1, v170
	v_mul_f32_e32 v219, 0x437f0000, v223
	v_rndne_f32_e32 v219, v219
	v_cvt_pk_u8_f32 v170, v219, 2, v170
	v_mul_f32_e32 v219, 0x437f0000, v225
	v_lshlrev_b64 v[146:147], 11, v[184:185]
	v_rndne_f32_e32 v219, v219
	v_lshl_add_u64 v[146:147], v[148:149], 0, v[146:147]
	v_cvt_pk_u8_f32 v221, v219, 3, v170
	v_add_f32_e32 v170, 1.0, v217
	global_store_dwordx2 v[146:147], v[220:221], off nt
	v_rcp_f32_e32 v170, v170
	v_add_f32_e32 v220, 1.0, v218
	v_rcp_f32_e32 v220, v220
	v_add_f32_e32 v222, 1.0, v154
	v_rcp_f32_e32 v222, v222
	v_add_f32_e32 v224, 1.0, v155
	v_mul_f32_e32 v170, 0x437f0000, v170
	v_rcp_f32_e32 v224, v224
	v_rndne_f32_e32 v170, v170
	v_mul_f32_e32 v220, 0x437f0000, v220
	v_add_f32_e32 v219, 1.0, v152
	v_cvt_pk_u8_f32 v170, v170, 0, 0
	v_rndne_f32_e32 v220, v220
	v_rcp_f32_e32 v219, v219
	v_add_f32_e32 v221, 1.0, v153
	v_cvt_pk_u8_f32 v170, v220, 1, v170
	v_mul_f32_e32 v220, 0x437f0000, v222
	v_rcp_f32_e32 v221, v221
	v_rndne_f32_e32 v220, v220
	v_add_f32_e32 v223, 1.0, v150
	v_cvt_pk_u8_f32 v170, v220, 2, v170
	v_mul_f32_e32 v220, 0x437f0000, v224
	v_rcp_f32_e32 v223, v223
	v_rndne_f32_e32 v220, v220
	v_add_f32_e32 v225, 1.0, v151
	v_cvt_pk_u8_f32 v220, v220, 3, v170
	v_mul_f32_e32 v170, 0x437f0000, v219
	v_rcp_f32_e32 v225, v225
	v_rndne_f32_e32 v170, v170
	v_mul_f32_e32 v219, 0x437f0000, v221
	v_cvt_pk_u8_f32 v170, v170, 0, 0
	v_rndne_f32_e32 v219, v219
	v_cvt_pk_u8_f32 v170, v219, 1, v170
	v_mul_f32_e32 v219, 0x437f0000, v223
	v_rndne_f32_e32 v219, v219
	v_cvt_pk_u8_f32 v170, v219, 2, v170
	v_mul_f32_e32 v219, 0x437f0000, v225
	v_rndne_f32_e32 v219, v219
	v_cvt_pk_u8_f32 v221, v219, 3, v170
	v_mul_f32_e32 v170, 0xbfb8aa3b, v110
	v_exp_f32_e32 v170, v170
	v_mul_f32_e32 v222, 0xbfb8aa3b, v111
	v_exp_f32_e32 v222, v222
	v_mul_f32_e32 v224, 0xbfb8aa3b, v112
	v_exp_f32_e32 v224, v224
	v_add_f32_e32 v170, 1.0, v170
	v_mul_f32_e32 v226, 0xbfb8aa3b, v113
	v_rcp_f32_e32 v170, v170
	v_add_f32_e32 v222, 1.0, v222
	v_exp_f32_e32 v226, v226
	v_mul_f32_e32 v219, 0xbfb8aa3b, v106
	v_rcp_f32_e32 v222, v222
	v_exp_f32_e32 v219, v219
	v_mul_f32_e32 v223, 0xbfb8aa3b, v107
	v_add_f32_e32 v224, 1.0, v224
	v_exp_f32_e32 v223, v223
	v_rcp_f32_e32 v224, v224
	v_mul_f32_e32 v225, 0xbfb8aa3b, v108
	v_add_f32_e32 v226, 1.0, v226
	v_mul_f32_e32 v170, 0x437f0000, v170
	v_exp_f32_e32 v225, v225
	v_rcp_f32_e32 v226, v226
	v_rndne_f32_e32 v170, v170
	v_mul_f32_e32 v222, 0x437f0000, v222
	v_add_f32_e32 v219, 1.0, v219
	v_mul_f32_e32 v227, 0xbfb8aa3b, v109
	v_cvt_pk_u8_f32 v170, v170, 0, 0
	v_rndne_f32_e32 v222, v222
	v_rcp_f32_e32 v219, v219
	v_add_f32_e32 v223, 1.0, v223
	v_exp_f32_e32 v227, v227
	v_cvt_pk_u8_f32 v170, v222, 1, v170
	v_mul_f32_e32 v222, 0x437f0000, v224
	v_rcp_f32_e32 v223, v223
	v_rndne_f32_e32 v222, v222
	v_add_f32_e32 v225, 1.0, v225
	v_cvt_pk_u8_f32 v170, v222, 2, v170
	v_mul_f32_e32 v222, 0x437f0000, v226
	v_rcp_f32_e32 v225, v225
	v_rndne_f32_e32 v222, v222
	v_add_f32_e32 v227, 1.0, v227
	v_cvt_pk_u8_f32 v222, v222, 3, v170
	v_mul_f32_e32 v170, 0x437f0000, v219
	v_rcp_f32_e32 v227, v227
	v_rndne_f32_e32 v170, v170
	v_mul_f32_e32 v219, 0x437f0000, v223
	v_cvt_pk_u8_f32 v170, v170, 0, 0
	v_rndne_f32_e32 v219, v219
	v_cvt_pk_u8_f32 v170, v219, 1, v170
	v_mul_f32_e32 v219, 0x437f0000, v225
	global_store_dwordx2 v[146:147], v[220:221], off offset:128 nt
	v_or_b32_e32 v220, 16, v184
	v_rndne_f32_e32 v219, v219
	v_ashrrev_i32_e32 v221, 31, v220
	v_cvt_pk_u8_f32 v170, v219, 2, v170
	v_mul_f32_e32 v219, 0x437f0000, v227
	v_lshlrev_b64 v[220:221], 11, v[220:221]
	v_rndne_f32_e32 v219, v219
	v_lshl_add_u64 v[220:221], v[148:149], 0, v[220:221]
	v_cvt_pk_u8_f32 v223, v219, 3, v170
	v_add_f32_e32 v170, 1.0, v215
	global_store_dwordx2 v[220:221], v[222:223], off nt
	v_rcp_f32_e32 v170, v170
	v_add_f32_e32 v222, 1.0, v216
	v_rcp_f32_e32 v222, v222
	v_add_f32_e32 v224, 1.0, v213
	v_rcp_f32_e32 v224, v224
	v_add_f32_e32 v226, 1.0, v214
	v_mul_f32_e32 v170, 0x437f0000, v170
	v_rcp_f32_e32 v226, v226
	v_rndne_f32_e32 v170, v170
	v_mul_f32_e32 v222, 0x437f0000, v222
	v_add_f32_e32 v219, 1.0, v211
	v_cvt_pk_u8_f32 v170, v170, 0, 0
	v_rndne_f32_e32 v222, v222
	v_rcp_f32_e32 v219, v219
	v_add_f32_e32 v223, 1.0, v212
	v_cvt_pk_u8_f32 v170, v222, 1, v170
	v_mul_f32_e32 v222, 0x437f0000, v224
	v_rcp_f32_e32 v223, v223
	v_rndne_f32_e32 v222, v222
	v_add_f32_e32 v225, 1.0, v209
	v_cvt_pk_u8_f32 v170, v222, 2, v170
	v_mul_f32_e32 v222, 0x437f0000, v226
	v_rcp_f32_e32 v225, v225
	v_rndne_f32_e32 v222, v222
	v_add_f32_e32 v227, 1.0, v210
	v_cvt_pk_u8_f32 v222, v222, 3, v170
	v_mul_f32_e32 v170, 0x437f0000, v219
	v_rcp_f32_e32 v227, v227
	v_rndne_f32_e32 v170, v170
	v_mul_f32_e32 v219, 0x437f0000, v223
	v_cvt_pk_u8_f32 v170, v170, 0, 0
	v_rndne_f32_e32 v219, v219
	v_cvt_pk_u8_f32 v170, v219, 1, v170
	v_mul_f32_e32 v219, 0x437f0000, v225
	v_rndne_f32_e32 v219, v219
	v_cvt_pk_u8_f32 v170, v219, 2, v170
	v_mul_f32_e32 v219, 0x437f0000, v227
	v_rndne_f32_e32 v219, v219
	v_cvt_pk_u8_f32 v223, v219, 3, v170
	v_mul_f32_e32 v170, 0xbfb8aa3b, v94
	global_store_dwordx2 v[220:221], v[222:223], off offset:128 nt
	v_exp_f32_e32 v170, v170
	v_mul_f32_e32 v222, 0xbfb8aa3b, v95
	v_exp_f32_e32 v222, v222
	v_mul_f32_e32 v224, 0xbfb8aa3b, v96
	v_exp_f32_e32 v224, v224
	v_add_f32_e32 v170, 1.0, v170
	v_mul_f32_e32 v226, 0xbfb8aa3b, v97
	v_rcp_f32_e32 v170, v170
	v_add_f32_e32 v222, 1.0, v222
	v_exp_f32_e32 v226, v226
	v_mul_f32_e32 v219, 0xbfb8aa3b, v90
	v_rcp_f32_e32 v222, v222
	v_exp_f32_e32 v219, v219
	v_mul_f32_e32 v223, 0xbfb8aa3b, v91
	v_add_f32_e32 v224, 1.0, v224
	v_exp_f32_e32 v223, v223
	v_rcp_f32_e32 v224, v224
	v_mul_f32_e32 v225, 0xbfb8aa3b, v92
	v_add_f32_e32 v226, 1.0, v226
	v_mul_f32_e32 v170, 0x437f0000, v170
	v_exp_f32_e32 v225, v225
	v_rcp_f32_e32 v226, v226
	v_rndne_f32_e32 v170, v170
	v_mul_f32_e32 v222, 0x437f0000, v222
	v_add_f32_e32 v219, 1.0, v219
	v_mul_f32_e32 v227, 0xbfb8aa3b, v93
	v_cvt_pk_u8_f32 v170, v170, 0, 0
	v_rndne_f32_e32 v222, v222
	v_rcp_f32_e32 v219, v219
	v_add_f32_e32 v223, 1.0, v223
	v_exp_f32_e32 v227, v227
	v_cvt_pk_u8_f32 v170, v222, 1, v170
	v_mul_f32_e32 v222, 0x437f0000, v224
	v_rcp_f32_e32 v223, v223
	v_rndne_f32_e32 v222, v222
	v_add_f32_e32 v225, 1.0, v225
	v_cvt_pk_u8_f32 v170, v222, 2, v170
	v_mul_f32_e32 v222, 0x437f0000, v226
	v_rcp_f32_e32 v225, v225
	v_rndne_f32_e32 v222, v222
	v_add_f32_e32 v227, 1.0, v227
	v_cvt_pk_u8_f32 v222, v222, 3, v170
	v_mul_f32_e32 v170, 0x437f0000, v219
	v_rcp_f32_e32 v227, v227
	v_rndne_f32_e32 v170, v170
	v_mul_f32_e32 v219, 0x437f0000, v223
	v_cvt_pk_u8_f32 v170, v170, 0, 0
	v_rndne_f32_e32 v219, v219
	v_cvt_pk_u8_f32 v170, v219, 1, v170
	v_mul_f32_e32 v219, 0x437f0000, v225
	v_or_b32_e32 v220, 32, v184
	v_rndne_f32_e32 v219, v219
	v_ashrrev_i32_e32 v221, 31, v220
	v_cvt_pk_u8_f32 v170, v219, 2, v170
	v_mul_f32_e32 v219, 0x437f0000, v227
	v_lshlrev_b64 v[220:221], 11, v[220:221]
	v_rndne_f32_e32 v219, v219
	v_lshl_add_u64 v[220:221], v[148:149], 0, v[220:221]
	v_cvt_pk_u8_f32 v223, v219, 3, v170
	v_add_f32_e32 v170, 1.0, v207
	global_store_dwordx2 v[220:221], v[222:223], off nt
	v_rcp_f32_e32 v170, v170
	v_add_f32_e32 v222, 1.0, v208
	v_rcp_f32_e32 v222, v222
	v_add_f32_e32 v224, 1.0, v205
	v_rcp_f32_e32 v224, v224
	v_add_f32_e32 v226, 1.0, v206
	v_mul_f32_e32 v170, 0x437f0000, v170
	v_rcp_f32_e32 v226, v226
	v_rndne_f32_e32 v170, v170
	v_mul_f32_e32 v222, 0x437f0000, v222
	v_add_f32_e32 v219, 1.0, v190
	v_cvt_pk_u8_f32 v170, v170, 0, 0
	v_rndne_f32_e32 v222, v222
	v_rcp_f32_e32 v219, v219
	v_add_f32_e32 v223, 1.0, v191
	v_cvt_pk_u8_f32 v170, v222, 1, v170
	v_mul_f32_e32 v222, 0x437f0000, v224
	v_rcp_f32_e32 v223, v223
	v_rndne_f32_e32 v222, v222
	v_add_f32_e32 v225, 1.0, v156
	v_cvt_pk_u8_f32 v170, v222, 2, v170
	v_mul_f32_e32 v222, 0x437f0000, v226
	v_rcp_f32_e32 v225, v225
	v_rndne_f32_e32 v222, v222
	v_add_f32_e32 v227, 1.0, v157
	v_cvt_pk_u8_f32 v222, v222, 3, v170
	v_mul_f32_e32 v170, 0x437f0000, v219
	v_rcp_f32_e32 v227, v227
	v_rndne_f32_e32 v170, v170
	v_mul_f32_e32 v219, 0x437f0000, v223
	v_cvt_pk_u8_f32 v170, v170, 0, 0
	v_rndne_f32_e32 v219, v219
	v_cvt_pk_u8_f32 v170, v219, 1, v170
	v_mul_f32_e32 v219, 0x437f0000, v225
	v_rndne_f32_e32 v219, v219
	v_cvt_pk_u8_f32 v170, v219, 2, v170
	v_mul_f32_e32 v219, 0x437f0000, v227
	v_rndne_f32_e32 v219, v219
	v_cvt_pk_u8_f32 v223, v219, 3, v170
	global_store_dwordx2 v[220:221], v[222:223], off offset:128 nt
	v_or_b32_e32 v220, 48, v184
	v_ashrrev_i32_e32 v221, 31, v220
	v_lshlrev_b64 v[220:221], 11, v[220:221]
	v_mul_f32_e32 v170, 0xbfb8aa3b, v78
	v_exp_f32_e32 v170, v170
	v_lshl_add_u64 v[148:149], v[148:149], 0, v[220:221]
	v_mul_f32_e32 v220, 0xbfb8aa3b, v79
	v_exp_f32_e32 v220, v220
	v_mul_f32_e32 v222, 0xbfb8aa3b, v80
	v_exp_f32_e32 v222, v222
	v_add_f32_e32 v170, 1.0, v170
	v_mul_f32_e32 v224, 0xbfb8aa3b, v81
	v_rcp_f32_e32 v170, v170
	v_add_f32_e32 v220, 1.0, v220
	v_exp_f32_e32 v224, v224
	v_mul_f32_e32 v219, 0xbfb8aa3b, v74
	v_rcp_f32_e32 v220, v220
	v_exp_f32_e32 v219, v219
	v_mul_f32_e32 v221, 0xbfb8aa3b, v75
	v_add_f32_e32 v222, 1.0, v222
	v_exp_f32_e32 v221, v221
	v_rcp_f32_e32 v222, v222
	v_mul_f32_e32 v223, 0xbfb8aa3b, v76
	v_add_f32_e32 v224, 1.0, v224
	v_mul_f32_e32 v170, 0x437f0000, v170
	v_exp_f32_e32 v223, v223
	v_rcp_f32_e32 v224, v224
	v_rndne_f32_e32 v170, v170
	v_mul_f32_e32 v220, 0x437f0000, v220
	v_add_f32_e32 v219, 1.0, v219
	v_mul_f32_e32 v225, 0xbfb8aa3b, v77
	v_cvt_pk_u8_f32 v170, v170, 0, 0
	v_rndne_f32_e32 v220, v220
	v_rcp_f32_e32 v219, v219
	v_add_f32_e32 v221, 1.0, v221
	v_exp_f32_e32 v225, v225
	v_cvt_pk_u8_f32 v170, v220, 1, v170
	v_mul_f32_e32 v220, 0x437f0000, v222
	v_rcp_f32_e32 v221, v221
	v_rndne_f32_e32 v220, v220
	v_add_f32_e32 v223, 1.0, v223
	v_cvt_pk_u8_f32 v170, v220, 2, v170
	v_mul_f32_e32 v220, 0x437f0000, v224
	v_rcp_f32_e32 v223, v223
	v_rndne_f32_e32 v220, v220
	v_add_f32_e32 v225, 1.0, v225
	v_cvt_pk_u8_f32 v220, v220, 3, v170
	v_mul_f32_e32 v170, 0x437f0000, v219
	v_rcp_f32_e32 v225, v225
	v_rndne_f32_e32 v170, v170
	v_mul_f32_e32 v219, 0x437f0000, v221
	v_cvt_pk_u8_f32 v170, v170, 0, 0
	v_rndne_f32_e32 v219, v219
	v_cvt_pk_u8_f32 v170, v219, 1, v170
	v_mul_f32_e32 v219, 0x437f0000, v223
	v_rndne_f32_e32 v219, v219
	v_cvt_pk_u8_f32 v170, v219, 2, v170
	v_mul_f32_e32 v219, 0x437f0000, v225
	v_rndne_f32_e32 v219, v219
	v_cvt_pk_u8_f32 v221, v219, 3, v170
	v_add_f32_e32 v170, 1.0, v188
	global_store_dwordx2 v[148:149], v[220:221], off nt
	v_rcp_f32_e32 v170, v170
	v_add_f32_e32 v220, 1.0, v189
	v_rcp_f32_e32 v220, v220
	v_add_f32_e32 v222, 1.0, v186
	v_rcp_f32_e32 v222, v222
	v_add_f32_e32 v224, 1.0, v187
	v_mul_f32_e32 v170, 0x437f0000, v170
	v_rcp_f32_e32 v224, v224
	v_rndne_f32_e32 v170, v170
	v_mul_f32_e32 v220, 0x437f0000, v220
	v_add_f32_e32 v219, 1.0, v160
	v_cvt_pk_u8_f32 v170, v170, 0, 0
	v_rndne_f32_e32 v220, v220
	v_rcp_f32_e32 v219, v219
	v_add_f32_e32 v221, 1.0, v161
	v_cvt_pk_u8_f32 v170, v220, 1, v170
	v_mul_f32_e32 v220, 0x437f0000, v222
	v_rcp_f32_e32 v221, v221
	v_rndne_f32_e32 v220, v220
	v_add_f32_e32 v223, 1.0, v158
	v_cvt_pk_u8_f32 v170, v220, 2, v170
	v_mul_f32_e32 v220, 0x437f0000, v224
	v_rcp_f32_e32 v223, v223
	v_rndne_f32_e32 v220, v220
	v_add_f32_e32 v225, 1.0, v159
	v_cvt_pk_u8_f32 v220, v220, 3, v170
	v_mul_f32_e32 v170, 0x437f0000, v219
	v_rcp_f32_e32 v225, v225
	v_rndne_f32_e32 v170, v170
	v_mul_f32_e32 v219, 0x437f0000, v221
	v_cvt_pk_u8_f32 v170, v170, 0, 0
	v_rndne_f32_e32 v219, v219
	v_cvt_pk_u8_f32 v170, v219, 1, v170
	v_mul_f32_e32 v219, 0x437f0000, v223
	v_rndne_f32_e32 v219, v219
	v_cvt_pk_u8_f32 v170, v219, 2, v170
	v_mul_f32_e32 v219, 0x437f0000, v225
	v_rndne_f32_e32 v219, v219
	v_cvt_pk_u8_f32 v221, v219, 3, v170
	s_cmpk_gt_i32 s53, 0x154f
	global_store_dwordx2 v[148:149], v[220:221], off offset:128 nt
	s_cbranch_scc1 .LBB0_413
	s_waitcnt vmcnt(8)
	global_store_dwordx4 v[248:249], v[114:117], off nt
	global_store_dwordx4 v[250:251], v[134:137], off nt
	global_store_dwordx4 v[252:253], v[138:141], off nt
	global_store_dwordx4 v[254:255], v[142:145], off nt

.LBB0_435:
	s_or_b64 exec, exec, s[6:7]
	s_cmpk_gt_i32 s53, 0x154f
	s_cbranch_scc1 .LBB0_458
	s_waitcnt vmcnt(4)
	global_store_dwordx4 v[248:249], v[114:117], off nt
	global_store_dwordx4 v[250:251], v[134:137], off nt
	global_store_dwordx4 v[252:253], v[138:141], off nt
	global_store_dwordx4 v[254:255], v[142:145], off nt
	s_branch .LBB0_458

.LBB0_443:
	v_and_b32_e32 v156, 0xfff, v154
	v_add_u32_e32 v154, s0, v156
	v_ashrrev_i32_e32 v155, 31, v154
	v_lshlrev_b64 v[154:155], 12, v[154:155]
	v_lshl_add_u64 v[154:155], s[50:51], 0, v[154:155]
	v_lshl_add_u64 v[154:155], v[170:171], 2, v[154:155]
	v_cmp_lt_u32_e32 vcc, s93, v156
	s_nop 1
	v_cndmask_b32_e32 v157, 0, v155, vcc
	v_cndmask_b32_e32 v156, 0, v154, vcc
	s_or_b64 exec, exec, s[6:7]
	v_cmp_ne_u64_e32 vcc, 0, v[156:157]
	s_and_saveexec_b64 s[6:7], vcc
	s_cbranch_execnz .LBB0_434
	s_branch .LBB0_435
.LBB0_458:
	v_mul_f32_e32 v150, 0xbfb8aa3b, v50
	v_exp_f32_e32 v150, v150
	v_mul_f32_e32 v151, 0xbfb8aa3b, v51
	v_exp_f32_e32 v151, v151
	v_mul_f32_e32 v146, 0xbfb8aa3b, v54
	v_add_f32_e32 v150, 1.0, v150
	v_rcp_f32_e32 v156, v150
	v_add_f32_e32 v150, 1.0, v151
	v_mul_f32_e32 v151, 0xbfb8aa3b, v52
	v_mul_f32_e32 v147, 0xbfb8aa3b, v55
	v_mul_f32_e32 v148, 0xbfb8aa3b, v56
	v_mul_f32_e32 v149, 0xbfb8aa3b, v57
	v_exp_f32_e32 v151, v151
	v_mul_f32_e32 v152, 0xbfb8aa3b, v53
	v_exp_f32_e32 v146, v146
	v_exp_f32_e32 v147, v147
	v_exp_f32_e32 v148, v148
	v_exp_f32_e32 v149, v149
	v_exp_f32_e32 v152, v152
	v_rcp_f32_e32 v157, v150
	v_add_f32_e32 v150, 1.0, v151
	v_add_f32_e32 v146, 1.0, v146
	v_add_f32_e32 v147, 1.0, v147
	v_add_f32_e32 v148, 1.0, v148
	v_add_f32_e32 v149, 1.0, v149
	v_rcp_f32_e32 v158, v150
	v_add_f32_e32 v150, 1.0, v152
	v_rcp_f32_e32 v146, v146
	v_rcp_f32_e32 v147, v147
	v_rcp_f32_e32 v148, v148
	v_rcp_f32_e32 v149, v149
	v_rcp_f32_e32 v159, v150
	v_add_u32_e32 v154, 0x80, v184
	v_ashrrev_i32_e32 v155, 31, v154
	v_lshlrev_b64 v[160:161], 11, v[154:155]
	v_pk_mul_f32 v[150:151], v[62:63], v[146:147]
	v_pk_mul_f32 v[152:153], v[64:65], v[148:149]
	v_pk_mul_f32 v[146:147], v[58:59], v[156:157]
	v_pk_mul_f32 v[148:149], v[60:61], v[158:159]
	v_lshl_add_u64 v[160:161], s[38:39], 0, v[160:161]
	v_cvt_pk_bf16_f32 v156, v150, v151
	v_cvt_pk_bf16_f32 v157, v152, v153
	v_cvt_pk_bf16_f32 v158, v146, v147
	v_cvt_pk_bf16_f32 v159, v148, v149
	v_lshl_add_u64 v[160:161], v[170:171], 1, v[160:161]
	s_and_b32 s0, s55, 0xffffff80
	global_store_dwordx4 v[160:161], v[156:159], off
	s_cmpk_lg_i32 s0, 0x7f80
	s_nop 0
	v_mov_b64_e32 v[156:157], 0
	s_cbranch_scc1 .LBB0_460
	v_add_u32_e32 v155, 0x3f8080, v184
	v_lshrrev_b32_e32 v155, 2, v155
	v_mul_lo_u32 v155, v155, 30
	v_add_lshl_u32 v156, v155, v174, 12
	v_mov_b32_e32 v157, v171
	v_lshl_add_u64 v[156:157], s[48:49], 0, v[156:157]
	v_lshl_add_u64 v[156:157], v[170:171], 2, v[156:157]

.LBB0_487:
	s_cmpk_lt_i32 s53, 0x1550
	s_cselect_b64 s[70:71], -1, 0
	s_and_b64 vcc, exec, s[70:71]
	s_cbranch_vccz .Lp1_nocp
	s_cmpk_lt_u32 s53, 0xf8
	s_cbranch_scc0 .Lcpl2_a
	s_mov_b32 s2, s53
	s_mov_b32 s3, 0x8421085
	s_movk_i32 s1, 0x3e00
	s_movk_i32 s33, 0x200
	s_mov_b64 s[68:69], s[16:17]
	s_add_u32 s100, s28, 0x8280000
	s_addc_u32 s101, s29, 0
	s_branch .Lcpl2_go
.Lcpl2_a:
	s_cmpk_lt_u32 s53, 0x4f0
	s_cbranch_scc0 .Lcpl2_b
	s_add_i32 s2, s53, 0xffffff08
	s_mov_b32 s3, 0x2040811
	s_mov_b32 s1, 0xfe00
	s_movk_i32 s33, 0x200
	s_mov_b64 s[68:69], s[18:19]
	s_add_u32 s100, s28, 0x9280000
	s_addc_u32 s101, s29, 0
	s_branch .Lcpl2_go
.Lcpl2_b:
	s_cmpk_lt_u32 s53, 0x14e8
	s_cbranch_scc0 .Lcpl2_c
	s_add_i32 s2, s53, 0xfffffb10
	s_mov_b32 s3, 0x804021
	s_mov_b32 s1, 0x3fe00
	s_movk_i32 s33, 0x200
	s_mov_b64 s[68:69], s[20:21]
	s_add_u32 s100, s28, 0xd280000
	s_addc_u32 s101, s29, 0
	s_branch .Lcpl2_go
.Lcpl2_c:
	s_add_i32 s2, s53, 0xffffeb18
	s_mov_b32 s3, 0x13b13b14
	s_movk_i32 s1, 0x1a00
	s_movk_i32 s33, 0x400
	s_mov_b64 s[68:69], s[22:23]
	s_mov_b64 s[100:101], s[48:49]
.Lcpl2_go:
	s_lshl_b32 s0, s2, 2
	s_mul_hi_u32 s0, s0, s3
	s_lshl_b32 s2, s2, 11
	s_mul_i32 s10, s0, s1
	s_sub_u32 s10, s2, s10
	s_mul_i32 s11, s0, s33
	s_add_u32 s11, s2, s11
	v_add_u32_e32 v114, s10, v192
	v_add_u32_e32 v134, s10, v193
	v_add_u32_e32 v138, s10, v194
	v_add_u32_e32 v142, s10, v195
	v_cmp_le_u32_e64 s[12:13], s1, v114
	v_cmp_le_u32_e64 s[24:25], s1, v134
	v_cmp_le_u32_e64 s[26:27], s1, v138
	v_cmp_le_u32_e64 vcc, s1, v142
	v_add_u32_e32 v114, s11, v192
	v_add_u32_e32 v134, s11, v193
	v_add_u32_e32 v138, s11, v194
	v_add_u32_e32 v142, s11, v195
	v_mov_b32_e32 v116, s33
	v_cndmask_b32_e64 v115, 0, v116, s[12:13]
	v_cndmask_b32_e64 v135, 0, v116, s[24:25]
	v_cndmask_b32_e64 v139, 0, v116, s[26:27]
	v_cndmask_b32_e64 v143, 0, v116, vcc
	v_add_u32_e32 v114, v114, v115
	v_add_u32_e32 v134, v134, v135
	v_add_u32_e32 v138, v138, v139
	v_add_u32_e32 v142, v142, v143
	v_mov_b32_e32 v115, 0
	v_mov_b32_e32 v135, 0
	v_mov_b32_e32 v139, 0
	v_mov_b32_e32 v143, 0
	v_lshl_add_u64 v[248:249], v[114:115], 4, s[100:101]
	v_lshl_add_u64 v[250:251], v[134:135], 4, s[100:101]
	v_lshl_add_u64 v[252:253], v[138:139], 4, s[100:101]
	v_lshl_add_u64 v[254:255], v[142:143], 4, s[100:101]
	v_add_u32_e32 v114, s33, v114
	v_add_u32_e32 v134, s33, v134
	v_add_u32_e32 v138, s33, v138
	v_add_u32_e32 v142, s33, v142
	v_lshl_add_u64 v[114:115], v[114:115], 4, s[68:69]
	v_lshl_add_u64 v[134:135], v[134:135], 4, s[68:69]
	v_lshl_add_u64 v[138:139], v[138:139], 4, s[68:69]
	v_lshl_add_u64 v[142:143], v[142:143], 4, s[68:69]
	global_load_dwordx4 v[114:117], v[114:115], off nt
	global_load_dwordx4 v[134:137], v[134:135], off nt
	global_load_dwordx4 v[138:141], v[138:139], off nt
	global_load_dwordx4 v[142:145], v[142:143], off nt
	s_branch .LBB0_509

.LBB0_494:
	v_and_b32_e32 v156, 0xfff, v154
	v_add_u32_e32 v154, v160, v156
	v_ashrrev_i32_e32 v155, 31, v154
	v_lshlrev_b64 v[154:155], 12, v[154:155]
	v_lshl_add_u64 v[154:155], s[50:51], 0, v[154:155]
	v_lshl_add_u64 v[154:155], v[170:171], 2, v[154:155]
	v_cmp_lt_u32_e32 vcc, s93, v156
	s_nop 1
	v_cndmask_b32_e32 v157, 0, v155, vcc
	v_cndmask_b32_e32 v156, 0, v154, vcc
	s_or_b64 exec, exec, s[6:7]
	v_cmp_ne_u64_e32 vcc, 0, v[156:157]
	s_and_saveexec_b64 s[6:7], vcc
	s_cbranch_execnz .LBB0_477
	s_branch .LBB0_478
	s_branch .LBB0_509

.LBB0_509:
	v_cndmask_b32_e64 v185, 1.0, v202, s[8:9]
	s_and_b64 vcc, exec, s[64:65]
	s_cbranch_vccz .LBB0_511
	v_pk_mul_f32 v[186:187], v[132:133], v[132:133]
	v_pk_mul_f32 v[188:189], v[130:131], v[130:131]
	v_mul_f32_e32 v205, v120, v120
	v_pk_mov_b32 v[190:191], v[188:189], v[186:187] op_sel:[1,0]
	v_mov_b32_e32 v189, v187
	v_pk_add_f32 v[186:187], v[190:191], v[188:189]
	v_pk_mul_f32 v[188:189], v[128:129], v[128:129]
	v_pk_mul_f32 v[190:191], v[126:127], v[126:127]
	v_pk_add_f32 v[186:187], v[186:187], v[186:187] op_sel:[0,1] op_sel_hi:[1,0]
	v_pk_mov_b32 v[206:207], v[190:191], v[188:189] op_sel:[1,0]
	v_mov_b32_e32 v191, v189
	v_pk_add_f32 v[188:189], v[206:207], v[190:191]
	v_mul_f32_e32 v190, v118, v118
	v_mul_f32_e32 v191, v119, v119
	v_pk_add_f32 v[188:189], v[188:189], v[188:189] op_sel:[0,1] op_sel_hi:[1,0]
	v_mov_b32_e32 v187, v190
	v_mov_b32_e32 v189, v191
	v_pk_add_f32 v[186:187], v[186:187], v[188:189]
	v_mul_f32_e32 v188, v123, v123
	v_mul_f32_e32 v190, v125, v125
	v_mul_f32_e32 v206, v121, v121
	v_pk_fma_f32 v[188:189], v[122:123], v[122:123], v[188:189] op_sel_hi:[1,1,0]
	v_pk_fma_f32 v[190:191], v[124:125], v[124:125], v[190:191] op_sel_hi:[1,1,0]
	v_mov_b32_e32 v189, v205
	v_mov_b32_e32 v191, v206
	v_pk_add_f32 v[188:189], v[188:189], v[190:191]
	s_nop 0
	v_pk_add_f32 v[186:187], v[186:187], v[188:189]
	v_and_b32_e32 v188, 64, v203
	v_add_f32_e32 v186, v186, v187
	v_xor_b32_e32 v187, 16, v203
	v_add_u32_e32 v188, 64, v188
	v_cmp_lt_i32_e32 vcc, v187, v188
	s_nop 1
	v_cndmask_b32_e32 v187, v203, v187, vcc
	v_lshlrev_b32_e32 v187, 2, v187
	ds_bpermute_b32 v187, v187, v186
	s_waitcnt lgkmcnt(0)
	v_add_f32_e32 v186, v186, v187
	v_xor_b32_e32 v187, 32, v203
	v_cmp_lt_i32_e32 vcc, v187, v188
	s_nop 1
	v_cndmask_b32_e32 v187, v203, v187, vcc
	v_lshlrev_b32_e32 v187, 2, v187
	ds_bpermute_b32 v187, v187, v186
	s_waitcnt lgkmcnt(0)
	v_add_f32_e32 v186, v186, v187
	v_fmamk_f32 v186, v186, 0x3c800000, v200
	v_rsq_f32_e32 v186, v186
	s_nop 0
	v_mul_f32_e32 v186, v185, v186
	v_pk_mul_f32 v[130:131], v[130:131], v[186:187] op_sel_hi:[1,0]
	v_pk_mul_f32 v[132:133], v[132:133], v[186:187] op_sel_hi:[1,0]
	v_pk_mul_f32 v[126:127], v[126:127], v[186:187] op_sel_hi:[1,0]
	v_pk_mul_f32 v[128:129], v[128:129], v[186:187] op_sel_hi:[1,0]
	v_pk_mul_f32 v[122:123], v[122:123], v[186:187] op_sel_hi:[1,0]
	v_pk_mul_f32 v[124:125], v[124:125], v[186:187] op_sel_hi:[1,0]
	v_pk_mul_f32 v[118:119], v[118:119], v[186:187] op_sel_hi:[1,0]
	v_pk_mul_f32 v[120:121], v[120:121], v[186:187] op_sel_hi:[1,0]
	s_waitcnt vmcnt(4)
	v_pk_mul_f32 v[132:133], v[152:153], v[132:133]
	v_pk_mul_f32 v[130:131], v[150:151], v[130:131]
	v_pk_mul_f32 v[128:129], v[148:149], v[128:129]
	v_pk_mul_f32 v[126:127], v[146:147], v[126:127]
	v_pk_mul_f32 v[124:125], v[160:161], v[124:125]
	v_pk_mul_f32 v[122:123], v[158:159], v[122:123]
	v_pk_mul_f32 v[120:121], v[156:157], v[120:121]
	v_pk_mul_f32 v[118:119], v[154:155], v[118:119]

.LBB0_522:
	v_pk_mul_f32 v[118:119], v[112:113], v[112:113]
	v_pk_mul_f32 v[120:121], v[110:111], v[110:111]
	s_nop 0
	v_pk_mov_b32 v[122:123], v[120:121], v[118:119] op_sel:[1,0]
	v_mov_b32_e32 v121, v119
	v_pk_add_f32 v[118:119], v[122:123], v[120:121]
	v_pk_mul_f32 v[120:121], v[108:109], v[108:109]
	v_pk_mul_f32 v[122:123], v[106:107], v[106:107]
	v_pk_add_f32 v[118:119], v[118:119], v[118:119] op_sel:[0,1] op_sel_hi:[1,0]
	v_pk_mov_b32 v[124:125], v[122:123], v[120:121] op_sel:[1,0]
	v_mov_b32_e32 v123, v121
	v_pk_add_f32 v[120:121], v[124:125], v[122:123]
	v_mul_f32_e32 v122, v98, v98
	v_mul_f32_e32 v123, v99, v99
	v_pk_add_f32 v[120:121], v[120:121], v[120:121] op_sel:[0,1] op_sel_hi:[1,0]
	v_mov_b32_e32 v119, v122
	v_mov_b32_e32 v121, v123
	v_pk_add_f32 v[118:119], v[118:119], v[120:121]
	v_mul_f32_e32 v120, v103, v103
	v_mul_f32_e32 v122, v105, v105
	v_mul_f32_e32 v124, v100, v100
	v_mul_f32_e32 v125, v101, v101
	v_pk_fma_f32 v[120:121], v[102:103], v[102:103], v[120:121] op_sel_hi:[1,1,0]
	v_pk_fma_f32 v[122:123], v[104:105], v[104:105], v[122:123] op_sel_hi:[1,1,0]
	v_mov_b32_e32 v121, v124
	v_mov_b32_e32 v123, v125
	v_pk_add_f32 v[120:121], v[120:121], v[122:123]
	s_nop 0
	v_pk_add_f32 v[118:119], v[118:119], v[120:121]
	v_and_b32_e32 v120, 64, v203
	v_add_f32_e32 v118, v118, v119
	v_xor_b32_e32 v119, 16, v203
	v_add_u32_e32 v120, 64, v120
	v_cmp_lt_i32_e32 vcc, v119, v120
	s_nop 1
	v_cndmask_b32_e32 v119, v203, v119, vcc
	v_lshlrev_b32_e32 v119, 2, v119
	ds_bpermute_b32 v119, v119, v118
	s_waitcnt lgkmcnt(0)
	v_add_f32_e32 v118, v118, v119
	v_xor_b32_e32 v119, 32, v203
	v_cmp_lt_i32_e32 vcc, v119, v120
	s_nop 1
	v_cndmask_b32_e32 v119, v203, v119, vcc
	v_lshlrev_b32_e32 v119, 2, v119
	ds_bpermute_b32 v119, v119, v118
	s_waitcnt lgkmcnt(0)
	v_add_f32_e32 v118, v118, v119
	v_fmamk_f32 v118, v118, 0x3c800000, v200
	v_rsq_f32_e32 v118, v118
	s_nop 0
	v_mul_f32_e32 v118, v185, v118
	v_pk_mul_f32 v[110:111], v[110:111], v[118:119] op_sel_hi:[1,0]
	v_pk_mul_f32 v[112:113], v[112:113], v[118:119] op_sel_hi:[1,0]
	v_pk_mul_f32 v[106:107], v[106:107], v[118:119] op_sel_hi:[1,0]
	v_pk_mul_f32 v[108:109], v[108:109], v[118:119] op_sel_hi:[1,0]
	v_pk_mul_f32 v[102:103], v[102:103], v[118:119] op_sel_hi:[1,0]
	v_pk_mul_f32 v[104:105], v[104:105], v[118:119] op_sel_hi:[1,0]
	v_pk_mul_f32 v[98:99], v[98:99], v[118:119] op_sel_hi:[1,0]
	v_pk_mul_f32 v[100:101], v[100:101], v[118:119] op_sel_hi:[1,0]
	s_nop 0
	v_pk_mul_f32 v[112:113], v[152:153], v[112:113]
	v_pk_mul_f32 v[110:111], v[150:151], v[110:111]
	v_pk_mul_f32 v[108:109], v[148:149], v[108:109]
	v_pk_mul_f32 v[106:107], v[146:147], v[106:107]
	v_pk_mul_f32 v[104:105], v[160:161], v[104:105]
	v_pk_mul_f32 v[102:103], v[158:159], v[102:103]
	v_pk_mul_f32 v[100:101], v[156:157], v[100:101]
	v_pk_mul_f32 v[98:99], v[154:155], v[98:99]

.LBB0_527:
	v_pk_mul_f32 v[98:99], v[96:97], v[96:97]
	v_pk_mul_f32 v[100:101], v[94:95], v[94:95]
	s_nop 0
	v_pk_mov_b32 v[102:103], v[100:101], v[98:99] op_sel:[1,0]
	v_mov_b32_e32 v101, v99
	v_pk_add_f32 v[98:99], v[102:103], v[100:101]
	v_pk_mul_f32 v[100:101], v[92:93], v[92:93]
	v_pk_mul_f32 v[102:103], v[90:91], v[90:91]
	v_pk_add_f32 v[98:99], v[98:99], v[98:99] op_sel:[0,1] op_sel_hi:[1,0]
	v_pk_mov_b32 v[104:105], v[102:103], v[100:101] op_sel:[1,0]
	v_mov_b32_e32 v103, v101
	v_pk_add_f32 v[100:101], v[104:105], v[102:103]
	v_mul_f32_e32 v102, v82, v82
	v_mul_f32_e32 v103, v83, v83
	v_pk_add_f32 v[100:101], v[100:101], v[100:101] op_sel:[0,1] op_sel_hi:[1,0]
	v_mov_b32_e32 v99, v102
	v_mov_b32_e32 v101, v103
	v_pk_add_f32 v[98:99], v[98:99], v[100:101]
	v_mul_f32_e32 v100, v87, v87
	v_mul_f32_e32 v102, v89, v89
	v_mul_f32_e32 v104, v84, v84
	v_mul_f32_e32 v105, v85, v85
	v_pk_fma_f32 v[100:101], v[86:87], v[86:87], v[100:101] op_sel_hi:[1,1,0]
	v_pk_fma_f32 v[102:103], v[88:89], v[88:89], v[102:103] op_sel_hi:[1,1,0]
	v_mov_b32_e32 v101, v104
	v_mov_b32_e32 v103, v105
	v_pk_add_f32 v[100:101], v[100:101], v[102:103]
	s_nop 0
	v_pk_add_f32 v[98:99], v[98:99], v[100:101]
	v_and_b32_e32 v100, 64, v203
	v_add_f32_e32 v98, v98, v99
	v_xor_b32_e32 v99, 16, v203
	v_add_u32_e32 v100, 64, v100
	v_cmp_lt_i32_e32 vcc, v99, v100
	s_nop 1
	v_cndmask_b32_e32 v99, v203, v99, vcc
	v_lshlrev_b32_e32 v99, 2, v99
	ds_bpermute_b32 v99, v99, v98
	s_waitcnt lgkmcnt(0)
	v_add_f32_e32 v98, v98, v99
	v_xor_b32_e32 v99, 32, v203
	v_cmp_lt_i32_e32 vcc, v99, v100
	s_nop 1
	v_cndmask_b32_e32 v99, v203, v99, vcc
	v_lshlrev_b32_e32 v99, 2, v99
	ds_bpermute_b32 v99, v99, v98
	s_waitcnt lgkmcnt(0)
	v_add_f32_e32 v98, v98, v99
	v_fmamk_f32 v98, v98, 0x3c800000, v200
	v_rsq_f32_e32 v98, v98
	s_nop 0
	v_mul_f32_e32 v98, v185, v98
	v_pk_mul_f32 v[94:95], v[94:95], v[98:99] op_sel_hi:[1,0]
	v_pk_mul_f32 v[96:97], v[96:97], v[98:99] op_sel_hi:[1,0]
	v_pk_mul_f32 v[90:91], v[90:91], v[98:99] op_sel_hi:[1,0]
	v_pk_mul_f32 v[92:93], v[92:93], v[98:99] op_sel_hi:[1,0]
	v_pk_mul_f32 v[86:87], v[86:87], v[98:99] op_sel_hi:[1,0]
	v_pk_mul_f32 v[88:89], v[88:89], v[98:99] op_sel_hi:[1,0]
	v_pk_mul_f32 v[82:83], v[82:83], v[98:99] op_sel_hi:[1,0]
	v_pk_mul_f32 v[84:85], v[84:85], v[98:99] op_sel_hi:[1,0]
	s_nop 0
	v_pk_mul_f32 v[96:97], v[152:153], v[96:97]
	v_pk_mul_f32 v[94:95], v[150:151], v[94:95]
	v_pk_mul_f32 v[92:93], v[148:149], v[92:93]
	v_pk_mul_f32 v[90:91], v[146:147], v[90:91]
	v_pk_mul_f32 v[88:89], v[160:161], v[88:89]
	v_pk_mul_f32 v[86:87], v[158:159], v[86:87]
	v_pk_mul_f32 v[84:85], v[156:157], v[84:85]
	v_pk_mul_f32 v[82:83], v[154:155], v[82:83]

.LBB0_532:
	v_pk_mul_f32 v[82:83], v[80:81], v[80:81]
	v_pk_mul_f32 v[84:85], v[78:79], v[78:79]
	s_nop 0
	v_pk_mov_b32 v[86:87], v[84:85], v[82:83] op_sel:[1,0]
	v_mov_b32_e32 v85, v83
	v_pk_add_f32 v[82:83], v[86:87], v[84:85]
	v_pk_mul_f32 v[84:85], v[76:77], v[76:77]
	v_pk_mul_f32 v[86:87], v[74:75], v[74:75]
	v_pk_add_f32 v[82:83], v[82:83], v[82:83] op_sel:[0,1] op_sel_hi:[1,0]
	v_pk_mov_b32 v[88:89], v[86:87], v[84:85] op_sel:[1,0]
	v_mov_b32_e32 v87, v85
	v_pk_add_f32 v[84:85], v[88:89], v[86:87]
	v_mul_f32_e32 v86, v66, v66
	v_mul_f32_e32 v87, v67, v67
	v_pk_add_f32 v[84:85], v[84:85], v[84:85] op_sel:[0,1] op_sel_hi:[1,0]
	v_mov_b32_e32 v83, v86
	v_mov_b32_e32 v85, v87
	v_pk_add_f32 v[82:83], v[82:83], v[84:85]
	v_mul_f32_e32 v84, v71, v71
	v_mul_f32_e32 v86, v73, v73
	v_mul_f32_e32 v88, v68, v68
	v_mul_f32_e32 v89, v69, v69
	v_pk_fma_f32 v[84:85], v[70:71], v[70:71], v[84:85] op_sel_hi:[1,1,0]
	v_pk_fma_f32 v[86:87], v[72:73], v[72:73], v[86:87] op_sel_hi:[1,1,0]
	v_mov_b32_e32 v85, v88
	v_mov_b32_e32 v87, v89
	v_pk_add_f32 v[84:85], v[84:85], v[86:87]
	s_nop 0
	v_pk_add_f32 v[82:83], v[82:83], v[84:85]
	v_and_b32_e32 v84, 64, v203
	v_add_f32_e32 v82, v82, v83
	v_xor_b32_e32 v83, 16, v203
	v_add_u32_e32 v84, 64, v84
	v_cmp_lt_i32_e32 vcc, v83, v84
	s_nop 1
	v_cndmask_b32_e32 v83, v203, v83, vcc
	v_lshlrev_b32_e32 v83, 2, v83
	ds_bpermute_b32 v83, v83, v82
	s_waitcnt lgkmcnt(0)
	v_add_f32_e32 v82, v82, v83
	v_xor_b32_e32 v83, 32, v203
	v_cmp_lt_i32_e32 vcc, v83, v84
	s_nop 1
	v_cndmask_b32_e32 v83, v203, v83, vcc
	v_lshlrev_b32_e32 v83, 2, v83
	ds_bpermute_b32 v83, v83, v82
	s_waitcnt lgkmcnt(0)
	v_add_f32_e32 v82, v82, v83
	v_fmamk_f32 v82, v82, 0x3c800000, v200
	v_rsq_f32_e32 v82, v82
	s_nop 0
	v_mul_f32_e32 v82, v185, v82
	v_pk_mul_f32 v[78:79], v[78:79], v[82:83] op_sel_hi:[1,0]
	v_pk_mul_f32 v[80:81], v[80:81], v[82:83] op_sel_hi:[1,0]
	v_pk_mul_f32 v[74:75], v[74:75], v[82:83] op_sel_hi:[1,0]
	v_pk_mul_f32 v[76:77], v[76:77], v[82:83] op_sel_hi:[1,0]
	v_pk_mul_f32 v[70:71], v[70:71], v[82:83] op_sel_hi:[1,0]
	v_pk_mul_f32 v[72:73], v[72:73], v[82:83] op_sel_hi:[1,0]
	v_pk_mul_f32 v[66:67], v[66:67], v[82:83] op_sel_hi:[1,0]
	v_pk_mul_f32 v[68:69], v[68:69], v[82:83] op_sel_hi:[1,0]
	s_nop 0
	v_pk_mul_f32 v[80:81], v[152:153], v[80:81]
	v_pk_mul_f32 v[78:79], v[150:151], v[78:79]
	v_pk_mul_f32 v[76:77], v[148:149], v[76:77]
	v_pk_mul_f32 v[74:75], v[146:147], v[74:75]
	v_pk_mul_f32 v[72:73], v[160:161], v[72:73]
	v_pk_mul_f32 v[70:71], v[158:159], v[70:71]
	v_pk_mul_f32 v[68:69], v[156:157], v[68:69]
	v_pk_mul_f32 v[66:67], v[154:155], v[66:67]

.LBB0_537:
	s_or_b64 exec, exec, s[10:11]
	s_andn2_b64 vcc, exec, s[70:71]
	s_cbranch_vccnz .LBB0_591
	s_waitcnt vmcnt(8)
	global_store_dwordx4 v[248:249], v[114:117], off nt
	global_store_dwordx4 v[250:251], v[134:137], off nt
	global_store_dwordx4 v[252:253], v[138:141], off nt
	global_store_dwordx4 v[254:255], v[142:145], off nt
	s_branch .LBB0_591

.LBB0_591:
	s_and_b64 vcc, exec, s[6:7]
	s_cbranch_vccnz .LBB0_593
	v_pk_mul_f32 v[66:67], v[64:65], v[64:65]
	v_pk_mul_f32 v[68:69], v[62:63], v[62:63]
	s_nop 0
	v_pk_mov_b32 v[70:71], v[68:69], v[66:67] op_sel:[1,0]
	v_mov_b32_e32 v69, v67
	v_pk_add_f32 v[66:67], v[70:71], v[68:69]
	v_pk_mul_f32 v[68:69], v[60:61], v[60:61]
	v_pk_mul_f32 v[70:71], v[58:59], v[58:59]
	v_pk_add_f32 v[66:67], v[66:67], v[66:67] op_sel:[0,1] op_sel_hi:[1,0]
	v_pk_mov_b32 v[72:73], v[70:71], v[68:69] op_sel:[1,0]
	v_mov_b32_e32 v71, v69
	v_pk_add_f32 v[68:69], v[72:73], v[70:71]
	v_mul_f32_e32 v70, v50, v50
	v_mul_f32_e32 v71, v51, v51
	v_pk_add_f32 v[68:69], v[68:69], v[68:69] op_sel:[0,1] op_sel_hi:[1,0]
	v_mov_b32_e32 v67, v70
	v_mov_b32_e32 v69, v71
	v_pk_add_f32 v[66:67], v[66:67], v[68:69]
	v_mul_f32_e32 v68, v55, v55
	v_mul_f32_e32 v70, v57, v57
	v_mul_f32_e32 v72, v52, v52
	v_mul_f32_e32 v73, v53, v53
	v_pk_fma_f32 v[68:69], v[54:55], v[54:55], v[68:69] op_sel_hi:[1,1,0]
	v_pk_fma_f32 v[70:71], v[56:57], v[56:57], v[70:71] op_sel_hi:[1,1,0]
	v_mov_b32_e32 v69, v72
	v_mov_b32_e32 v71, v73
	v_pk_add_f32 v[68:69], v[68:69], v[70:71]
	s_nop 0
	v_pk_add_f32 v[66:67], v[66:67], v[68:69]
	v_and_b32_e32 v68, 64, v203
	v_add_f32_e32 v66, v66, v67
	v_xor_b32_e32 v67, 16, v203
	v_add_u32_e32 v68, 64, v68
	v_cmp_lt_i32_e32 vcc, v67, v68
	s_nop 1
	v_cndmask_b32_e32 v67, v203, v67, vcc
	v_lshlrev_b32_e32 v67, 2, v67
	ds_bpermute_b32 v67, v67, v66
	s_waitcnt lgkmcnt(0)
	v_add_f32_e32 v66, v66, v67
	v_xor_b32_e32 v67, 32, v203
	v_cmp_lt_i32_e32 vcc, v67, v68
	s_nop 1
	v_cndmask_b32_e32 v67, v203, v67, vcc
	v_lshlrev_b32_e32 v67, 2, v67
	ds_bpermute_b32 v67, v67, v66
	s_waitcnt lgkmcnt(0)
	v_add_f32_e32 v66, v66, v67
	v_fmamk_f32 v66, v66, 0x3c800000, v200
	v_rsq_f32_e32 v66, v66
	s_nop 0
	v_mul_f32_e32 v66, v185, v66
	v_pk_mul_f32 v[62:63], v[62:63], v[66:67] op_sel_hi:[1,0]
	v_pk_mul_f32 v[64:65], v[64:65], v[66:67] op_sel_hi:[1,0]
	v_pk_mul_f32 v[58:59], v[58:59], v[66:67] op_sel_hi:[1,0]
	v_pk_mul_f32 v[60:61], v[60:61], v[66:67] op_sel_hi:[1,0]
	v_pk_mul_f32 v[54:55], v[54:55], v[66:67] op_sel_hi:[1,0]
	v_pk_mul_f32 v[56:57], v[56:57], v[66:67] op_sel_hi:[1,0]
	v_pk_mul_f32 v[50:51], v[50:51], v[66:67] op_sel_hi:[1,0]
	v_pk_mul_f32 v[52:53], v[52:53], v[66:67] op_sel_hi:[1,0]
	s_nop 0
	v_pk_mul_f32 v[64:65], v[152:153], v[64:65]
	v_pk_mul_f32 v[62:63], v[150:151], v[62:63]
	v_pk_mul_f32 v[60:61], v[148:149], v[60:61]
	v_pk_mul_f32 v[58:59], v[146:147], v[58:59]
	v_pk_mul_f32 v[56:57], v[160:161], v[56:57]
	v_pk_mul_f32 v[54:55], v[158:159], v[54:55]
	v_pk_mul_f32 v[52:53], v[156:157], v[52:53]
	v_pk_mul_f32 v[50:51], v[154:155], v[50:51]

.LBB0_604:
	v_pk_mul_f32 v[50:51], v[48:49], v[48:49]
	v_pk_mul_f32 v[52:53], v[46:47], v[46:47]
	s_nop 0
	v_pk_mov_b32 v[54:55], v[52:53], v[50:51] op_sel:[1,0]
	v_mov_b32_e32 v53, v51
	v_pk_add_f32 v[50:51], v[54:55], v[52:53]
	v_pk_mul_f32 v[52:53], v[44:45], v[44:45]
	v_pk_mul_f32 v[54:55], v[42:43], v[42:43]
	v_pk_add_f32 v[50:51], v[50:51], v[50:51] op_sel:[0,1] op_sel_hi:[1,0]
	v_pk_mov_b32 v[56:57], v[54:55], v[52:53] op_sel:[1,0]
	v_mov_b32_e32 v55, v53
	v_pk_add_f32 v[52:53], v[56:57], v[54:55]
	v_mul_f32_e32 v54, v34, v34
	v_mul_f32_e32 v55, v35, v35
	v_pk_add_f32 v[52:53], v[52:53], v[52:53] op_sel:[0,1] op_sel_hi:[1,0]
	v_mov_b32_e32 v51, v54
	v_mov_b32_e32 v53, v55
	v_pk_add_f32 v[50:51], v[50:51], v[52:53]
	v_mul_f32_e32 v52, v39, v39
	v_mul_f32_e32 v54, v41, v41
	v_mul_f32_e32 v56, v36, v36
	v_mul_f32_e32 v57, v37, v37
	v_pk_fma_f32 v[52:53], v[38:39], v[38:39], v[52:53] op_sel_hi:[1,1,0]
	v_pk_fma_f32 v[54:55], v[40:41], v[40:41], v[54:55] op_sel_hi:[1,1,0]
	v_mov_b32_e32 v53, v56
	v_mov_b32_e32 v55, v57
	v_pk_add_f32 v[52:53], v[52:53], v[54:55]
	s_nop 0
	v_pk_add_f32 v[50:51], v[50:51], v[52:53]
	v_and_b32_e32 v52, 64, v203
	v_add_f32_e32 v50, v50, v51
	v_xor_b32_e32 v51, 16, v203
	v_add_u32_e32 v52, 64, v52
	v_cmp_lt_i32_e32 vcc, v51, v52
	s_nop 1
	v_cndmask_b32_e32 v51, v203, v51, vcc
	v_lshlrev_b32_e32 v51, 2, v51
	ds_bpermute_b32 v51, v51, v50
	s_waitcnt lgkmcnt(0)
	v_add_f32_e32 v50, v50, v51
	v_xor_b32_e32 v51, 32, v203
	v_cmp_lt_i32_e32 vcc, v51, v52
	s_nop 1
	v_cndmask_b32_e32 v51, v203, v51, vcc
	v_lshlrev_b32_e32 v51, 2, v51
	ds_bpermute_b32 v51, v51, v50
	s_waitcnt lgkmcnt(0)
	v_add_f32_e32 v50, v50, v51
	v_fmamk_f32 v50, v50, 0x3c800000, v200
	v_rsq_f32_e32 v50, v50
	s_nop 0
	v_mul_f32_e32 v50, v185, v50
	v_pk_mul_f32 v[46:47], v[46:47], v[50:51] op_sel_hi:[1,0]
	v_pk_mul_f32 v[48:49], v[48:49], v[50:51] op_sel_hi:[1,0]
	v_pk_mul_f32 v[42:43], v[42:43], v[50:51] op_sel_hi:[1,0]
	v_pk_mul_f32 v[44:45], v[44:45], v[50:51] op_sel_hi:[1,0]
	v_pk_mul_f32 v[38:39], v[38:39], v[50:51] op_sel_hi:[1,0]
	v_pk_mul_f32 v[40:41], v[40:41], v[50:51] op_sel_hi:[1,0]
	v_pk_mul_f32 v[34:35], v[34:35], v[50:51] op_sel_hi:[1,0]
	v_pk_mul_f32 v[36:37], v[36:37], v[50:51] op_sel_hi:[1,0]
	s_nop 0
	v_pk_mul_f32 v[48:49], v[152:153], v[48:49]
	v_pk_mul_f32 v[46:47], v[150:151], v[46:47]
	v_pk_mul_f32 v[44:45], v[148:149], v[44:45]
	v_pk_mul_f32 v[42:43], v[146:147], v[42:43]
	v_pk_mul_f32 v[40:41], v[160:161], v[40:41]
	v_pk_mul_f32 v[38:39], v[158:159], v[38:39]
	v_pk_mul_f32 v[36:37], v[156:157], v[36:37]
	v_pk_mul_f32 v[34:35], v[154:155], v[34:35]

.LBB0_609:
	v_pk_mul_f32 v[34:35], v[32:33], v[32:33]
	v_pk_mul_f32 v[36:37], v[30:31], v[30:31]
	s_nop 0
	v_pk_mov_b32 v[38:39], v[36:37], v[34:35] op_sel:[1,0]
	v_mov_b32_e32 v37, v35
	v_pk_add_f32 v[34:35], v[38:39], v[36:37]
	v_pk_mul_f32 v[36:37], v[28:29], v[28:29]
	v_pk_mul_f32 v[38:39], v[26:27], v[26:27]
	v_pk_add_f32 v[34:35], v[34:35], v[34:35] op_sel:[0,1] op_sel_hi:[1,0]
	v_pk_mov_b32 v[40:41], v[38:39], v[36:37] op_sel:[1,0]
	v_mov_b32_e32 v39, v37
	v_pk_add_f32 v[36:37], v[40:41], v[38:39]
	v_mul_f32_e32 v38, v18, v18
	v_mul_f32_e32 v39, v19, v19
	v_pk_add_f32 v[36:37], v[36:37], v[36:37] op_sel:[0,1] op_sel_hi:[1,0]
	v_mov_b32_e32 v35, v38
	v_mov_b32_e32 v37, v39
	v_pk_add_f32 v[34:35], v[34:35], v[36:37]
	v_mul_f32_e32 v36, v23, v23
	v_mul_f32_e32 v38, v25, v25
	v_mul_f32_e32 v40, v20, v20
	v_mul_f32_e32 v41, v21, v21
	v_pk_fma_f32 v[36:37], v[22:23], v[22:23], v[36:37] op_sel_hi:[1,1,0]
	v_pk_fma_f32 v[38:39], v[24:25], v[24:25], v[38:39] op_sel_hi:[1,1,0]
	v_mov_b32_e32 v37, v40
	v_mov_b32_e32 v39, v41
	v_pk_add_f32 v[36:37], v[36:37], v[38:39]
	s_nop 0
	v_pk_add_f32 v[34:35], v[34:35], v[36:37]
	v_and_b32_e32 v36, 64, v203
	v_add_f32_e32 v34, v34, v35
	v_xor_b32_e32 v35, 16, v203
	v_add_u32_e32 v36, 64, v36
	v_cmp_lt_i32_e32 vcc, v35, v36
	s_nop 1
	v_cndmask_b32_e32 v35, v203, v35, vcc
	v_lshlrev_b32_e32 v35, 2, v35
	ds_bpermute_b32 v35, v35, v34
	s_waitcnt lgkmcnt(0)
	v_add_f32_e32 v34, v34, v35
	v_xor_b32_e32 v35, 32, v203
	v_cmp_lt_i32_e32 vcc, v35, v36
	s_nop 1
	v_cndmask_b32_e32 v35, v203, v35, vcc
	v_lshlrev_b32_e32 v35, 2, v35
	ds_bpermute_b32 v35, v35, v34
	s_waitcnt lgkmcnt(0)
	v_add_f32_e32 v34, v34, v35
	v_fmamk_f32 v34, v34, 0x3c800000, v200
	v_rsq_f32_e32 v34, v34
	s_nop 0
	v_mul_f32_e32 v34, v185, v34
	v_pk_mul_f32 v[30:31], v[30:31], v[34:35] op_sel_hi:[1,0]
	v_pk_mul_f32 v[32:33], v[32:33], v[34:35] op_sel_hi:[1,0]
	v_pk_mul_f32 v[26:27], v[26:27], v[34:35] op_sel_hi:[1,0]
	v_pk_mul_f32 v[28:29], v[28:29], v[34:35] op_sel_hi:[1,0]
	v_pk_mul_f32 v[22:23], v[22:23], v[34:35] op_sel_hi:[1,0]
	v_pk_mul_f32 v[24:25], v[24:25], v[34:35] op_sel_hi:[1,0]
	v_pk_mul_f32 v[18:19], v[18:19], v[34:35] op_sel_hi:[1,0]
	v_pk_mul_f32 v[20:21], v[20:21], v[34:35] op_sel_hi:[1,0]
	s_nop 0
	v_pk_mul_f32 v[32:33], v[152:153], v[32:33]
	v_pk_mul_f32 v[30:31], v[150:151], v[30:31]
	v_pk_mul_f32 v[28:29], v[148:149], v[28:29]
	v_pk_mul_f32 v[26:27], v[146:147], v[26:27]
	v_pk_mul_f32 v[24:25], v[160:161], v[24:25]
	v_pk_mul_f32 v[22:23], v[158:159], v[22:23]
	v_pk_mul_f32 v[20:21], v[156:157], v[20:21]
	v_pk_mul_f32 v[18:19], v[154:155], v[18:19]

.LBB0_614:
	v_pk_mul_f32 v[18:19], v[16:17], v[16:17]
	v_pk_mul_f32 v[20:21], v[14:15], v[14:15]
	s_nop 0
	v_pk_mov_b32 v[22:23], v[20:21], v[18:19] op_sel:[1,0]
	v_mov_b32_e32 v21, v19
	v_pk_add_f32 v[18:19], v[22:23], v[20:21]
	v_pk_mul_f32 v[20:21], v[12:13], v[12:13]
	v_pk_mul_f32 v[22:23], v[10:11], v[10:11]
	v_pk_add_f32 v[18:19], v[18:19], v[18:19] op_sel:[0,1] op_sel_hi:[1,0]
	v_pk_mov_b32 v[24:25], v[22:23], v[20:21] op_sel:[1,0]
	v_mov_b32_e32 v23, v21
	v_pk_add_f32 v[20:21], v[24:25], v[22:23]
	v_mul_f32_e32 v22, v2, v2
	v_mul_f32_e32 v23, v3, v3
	v_pk_add_f32 v[20:21], v[20:21], v[20:21] op_sel:[0,1] op_sel_hi:[1,0]
	v_mov_b32_e32 v19, v22
	v_mov_b32_e32 v21, v23
	v_pk_add_f32 v[18:19], v[18:19], v[20:21]
	v_mul_f32_e32 v20, v7, v7
	v_mul_f32_e32 v22, v9, v9
	v_mul_f32_e32 v24, v4, v4
	v_mul_f32_e32 v25, v5, v5
	v_pk_fma_f32 v[20:21], v[6:7], v[6:7], v[20:21] op_sel_hi:[1,1,0]
	v_pk_fma_f32 v[22:23], v[8:9], v[8:9], v[22:23] op_sel_hi:[1,1,0]
	v_mov_b32_e32 v21, v24
	v_mov_b32_e32 v23, v25
	v_pk_add_f32 v[20:21], v[20:21], v[22:23]
	s_nop 0
	v_pk_add_f32 v[18:19], v[18:19], v[20:21]
	v_and_b32_e32 v20, 64, v203
	v_add_f32_e32 v18, v18, v19
	v_xor_b32_e32 v19, 16, v203
	v_add_u32_e32 v20, 64, v20
	v_cmp_lt_i32_e32 vcc, v19, v20
	s_nop 1
	v_cndmask_b32_e32 v19, v203, v19, vcc
	v_lshlrev_b32_e32 v19, 2, v19
	ds_bpermute_b32 v19, v19, v18
	s_waitcnt lgkmcnt(0)
	v_add_f32_e32 v18, v18, v19
	v_xor_b32_e32 v19, 32, v203
	v_cmp_lt_i32_e32 vcc, v19, v20
	s_nop 1
	v_cndmask_b32_e32 v19, v203, v19, vcc
	v_lshlrev_b32_e32 v19, 2, v19
	ds_bpermute_b32 v19, v19, v18
	s_waitcnt lgkmcnt(0)
	v_add_f32_e32 v18, v18, v19
	v_fmamk_f32 v18, v18, 0x3c800000, v200
	v_rsq_f32_e32 v18, v18
	s_nop 0
	v_mul_f32_e32 v18, v185, v18
	v_pk_mul_f32 v[14:15], v[14:15], v[18:19] op_sel_hi:[1,0]
	v_pk_mul_f32 v[16:17], v[16:17], v[18:19] op_sel_hi:[1,0]
	v_pk_mul_f32 v[10:11], v[10:11], v[18:19] op_sel_hi:[1,0]
	v_pk_mul_f32 v[12:13], v[12:13], v[18:19] op_sel_hi:[1,0]
	v_pk_mul_f32 v[6:7], v[6:7], v[18:19] op_sel_hi:[1,0]
	v_pk_mul_f32 v[8:9], v[8:9], v[18:19] op_sel_hi:[1,0]
	v_pk_mul_f32 v[2:3], v[2:3], v[18:19] op_sel_hi:[1,0]
	v_pk_mul_f32 v[4:5], v[4:5], v[18:19] op_sel_hi:[1,0]
	s_nop 0
	v_pk_mul_f32 v[16:17], v[152:153], v[16:17]
	v_pk_mul_f32 v[14:15], v[150:151], v[14:15]
	v_pk_mul_f32 v[12:13], v[148:149], v[12:13]
	v_pk_mul_f32 v[10:11], v[146:147], v[10:11]
	v_pk_mul_f32 v[8:9], v[160:161], v[8:9]
	v_pk_mul_f32 v[6:7], v[158:159], v[6:7]
	v_pk_mul_f32 v[4:5], v[156:157], v[4:5]
	v_pk_mul_f32 v[2:3], v[154:155], v[2:3]

.LBB0_1011:
	s_mul_i32 s5, s5, s3
	v_cvt_f32_u32_e32 v158, s5
	s_add_i32 s4, s4, s2
	s_lshl_b32 s4, s4, 11
	s_sub_i32 s8, 0, s5
	v_rcp_iflag_f32_e32 v158, v158
	s_ashr_i32 s9, s4, 31
	s_abs_i32 s39, s4
	v_add_u32_e32 v160, s4, v218
	v_mul_f32_e32 v158, 0x4f7ffffe, v158
	v_cvt_u32_f32_e32 v158, v158
	v_mov_b32_e32 v159, s5
	v_readfirstlane_b32 s4, v158
	s_mul_i32 s8, s8, s4
	s_mul_hi_u32 s8, s4, s8
	s_add_i32 s4, s4, s8
	s_mul_hi_u32 s4, s39, s4
	s_mul_i32 s8, s4, s5
	s_sub_i32 s8, s39, s8
	s_add_i32 s44, s4, 1
	s_sub_i32 s39, s8, s5
	s_cmp_ge_u32 s8, s5
	s_cselect_b32 s4, s44, s4
	s_cselect_b32 s8, s39, s8
	s_add_i32 s39, s4, 1
	s_cmp_ge_u32 s8, s5
	s_cselect_b32 s4, s39, s4
	s_xor_b32 s4, s4, s9
	s_sub_i32 s4, s4, s9
	s_mul_i32 s8, s4, s5
	v_subrev_u32_e32 v158, s8, v160
	v_cmp_le_i32_e32 vcc, s5, v158
	s_nop 1
	v_cndmask_b32_e32 v159, 0, v159, vcc
	v_sub_u32_e32 v158, v158, v159
	v_mov_b32_e32 v159, s4
	v_addc_co_u32_e32 v159, vcc, 0, v159, vcc
	s_mul_i32 s4, s22, s3
	v_mad_u64_u32 v[158:159], s[4:5], s4, v159, v[158:159]
	v_mov_b32_e32 v159, v185
	v_lshl_add_u64 v[158:159], v[158:159], 4, s[10:11]
	s_lshl_b32 s22, s3, 6
	v_lshl_add_u64 v[158:159], v[158:159], 0, s[22:23]
	global_load_dwordx4 v[158:161], v[158:159], off nt
	s_branch .LBB0_1012

.LBB0_1012:
	v_lshl_or_b32 v224, s0, 7, v214
	v_and_b32_e32 v197, 64, v181
	v_xor_b32_e32 v199, 16, v181
	v_add_u32_e32 v197, 64, v197
	v_cmp_lt_i32_e32 vcc, v199, v197
	s_waitcnt vmcnt(4)
	v_mov_b32_e32 v226, v175
	v_mov_b32_e32 v227, v176
	v_mov_b32_e32 v175, v177
	v_cndmask_b32_e32 v199, v181, v199, vcc
	v_pk_add_f32 v[174:175], v[226:227], v[174:175]
	v_lshlrev_b32_e32 v199, 2, v199
	v_add_f32_e32 v175, v174, v175
	ds_bpermute_b32 v176, v199, v175
	v_xor_b32_e32 v174, 32, v181
	v_cmp_lt_i32_e32 vcc, v174, v197
	v_ashrrev_i32_e32 v225, 31, v224
	s_waitcnt lgkmcnt(0)
	v_add_f32_e32 v175, v175, v176
	v_cndmask_b32_e32 v174, v181, v174, vcc
	v_lshlrev_b32_e32 v174, 2, v174
	ds_bpermute_b32 v176, v174, v175
	s_waitcnt lgkmcnt(0)
	v_add_f32_e32 v175, v175, v176
	v_fmamk_f32 v175, v175, 0x3a800000, v222
	v_rsq_f32_e32 v176, v175
	s_nop 0
	v_pk_mul_f32 v[142:143], v[142:143], v[176:177] op_sel_hi:[1,0]
	s_nop 0
	v_mul_f32_e32 v175, 0xbfb8aa3b, v142
	v_mul_f32_e32 v177, 0xbfb8aa3b, v143
	v_exp_f32_e32 v175, v175
	v_exp_f32_e32 v177, v177
	v_add_f32_e32 v175, 1.0, v175
	v_add_f32_e32 v177, 1.0, v177
	v_rcp_f32_e32 v226, v175
	v_rcp_f32_e32 v227, v177
	v_pk_mul_f32 v[144:145], v[144:145], v[176:177] op_sel_hi:[1,0]
	v_pk_mul_f32 v[138:139], v[138:139], v[176:177] op_sel_hi:[1,0]
	v_mul_f32_e32 v175, 0xbfb8aa3b, v144
	v_pk_mul_f32 v[142:143], v[142:143], v[226:227]
	v_exp_f32_e32 v175, v175
	v_pk_mul_f32 v[138:139], v[138:139], v[142:143]
	v_mul_f32_e32 v142, 0xbfb8aa3b, v145
	v_exp_f32_e32 v143, v142
	v_pk_mul_f32 v[134:135], v[134:135], v[176:177] op_sel_hi:[1,0]
	v_add_f32_e32 v142, 1.0, v175
	v_mul_f32_e32 v175, 0xbfb8aa3b, v134
	v_pk_mul_f32 v[140:141], v[140:141], v[176:177] op_sel_hi:[1,0]
	v_add_f32_e32 v143, 1.0, v143
	v_exp_f32_e32 v175, v175
	v_mul_f32_e32 v177, 0xbfb8aa3b, v135
	v_rcp_f32_e32 v142, v142
	v_exp_f32_e32 v177, v177
	v_rcp_f32_e32 v143, v143
	v_add_f32_e32 v175, 1.0, v175
	v_rcp_f32_e32 v226, v175
	v_add_f32_e32 v175, 1.0, v177
	v_pk_mul_f32 v[142:143], v[144:145], v[142:143]
	v_pk_mul_f32 v[136:137], v[136:137], v[176:177] op_sel_hi:[1,0]
	v_rcp_f32_e32 v227, v175
	v_pk_mul_f32 v[140:141], v[140:141], v[142:143]
	v_mul_f32_e32 v142, 0xbfb8aa3b, v136
	v_mul_f32_e32 v143, 0xbfb8aa3b, v137
	v_exp_f32_e32 v142, v142
	v_exp_f32_e32 v143, v143
	v_pk_mul_f32 v[130:131], v[130:131], v[176:177] op_sel_hi:[1,0]
	v_pk_mul_f32 v[134:135], v[134:135], v[226:227]
	v_pk_mul_f32 v[132:133], v[132:133], v[176:177] op_sel_hi:[1,0]
	v_pk_mul_f32 v[130:131], v[130:131], v[134:135]
	v_add_f32_e32 v134, 1.0, v142
	v_add_f32_e32 v135, 1.0, v143
	v_mov_b32_e32 v142, v171
	v_mov_b32_e32 v143, v172
	v_mov_b32_e32 v171, v173
	v_pk_add_f32 v[142:143], v[142:143], v[170:171]
	v_rcp_f32_e32 v134, v134
	v_add_f32_e32 v142, v142, v143
	v_rcp_f32_e32 v135, v135
	ds_bpermute_b32 v143, v199, v142
	v_pk_mul_f32 v[134:135], v[136:137], v[134:135]
	s_nop 0
	v_pk_mul_f32 v[132:133], v[132:133], v[134:135]
	v_cvt_pk_bf16_f32 v134, v138, v139
	s_waitcnt lgkmcnt(0)
	v_add_f32_e32 v138, v142, v143
	ds_bpermute_b32 v139, v174, v138
	v_cvt_pk_bf16_f32 v136, v130, v131
	v_cvt_pk_bf16_f32 v137, v132, v133
	v_mov_b64_e32 v[132:133], s[26:27]
	v_cvt_pk_bf16_f32 v135, v140, v141
	s_waitcnt lgkmcnt(0)
	v_add_f32_e32 v130, v138, v139
	v_fmamk_f32 v130, v130, 0x3a800000, v222
	v_rsq_f32_e32 v138, v130
	v_mad_i64_i32 v[140:141], s[4:5], v210, s68, v[132:133]
	v_lshlrev_b64 v[130:131], 1, v[224:225]
	v_pk_mul_f32 v[126:127], v[126:127], v[138:139] op_sel_hi:[1,0]
	v_lshl_add_u64 v[140:141], v[140:141], 0, v[130:131]
	v_mul_f32_e32 v139, 0xbfb8aa3b, v126
	v_exp_f32_e32 v139, v139
	global_store_dwordx4 v[140:141], v[134:137], off
	v_pk_mul_f32 v[128:129], v[128:129], v[138:139] op_sel_hi:[1,0]
	s_nop 0
	v_mul_f32_e32 v134, 0xbfb8aa3b, v127
	v_exp_f32_e32 v135, v134
	v_mul_f32_e32 v136, 0xbfb8aa3b, v128
	v_mul_f32_e32 v137, 0xbfb8aa3b, v129
	v_exp_f32_e32 v136, v136
	v_exp_f32_e32 v137, v137
	v_add_f32_e32 v134, 1.0, v139
	v_add_f32_e32 v135, 1.0, v135
	v_rcp_f32_e32 v134, v134
	v_rcp_f32_e32 v135, v135
	v_add_f32_e32 v136, 1.0, v136
	v_add_f32_e32 v137, 1.0, v137
	v_rcp_f32_e32 v136, v136
	v_rcp_f32_e32 v137, v137
	v_pk_mul_f32 v[118:119], v[118:119], v[138:139] op_sel_hi:[1,0]
	v_pk_mul_f32 v[126:127], v[126:127], v[134:135]
	v_pk_mul_f32 v[120:121], v[120:121], v[138:139] op_sel_hi:[1,0]
	v_pk_mul_f32 v[118:119], v[118:119], v[126:127]
	v_pk_mul_f32 v[126:127], v[128:129], v[136:137]
	v_pk_mul_f32 v[122:123], v[122:123], v[138:139] op_sel_hi:[1,0]
	v_pk_mul_f32 v[120:121], v[120:121], v[126:127]
	v_mul_f32_e32 v128, 0xbfb8aa3b, v122
	v_mul_f32_e32 v126, 0xbfb8aa3b, v123
	v_exp_f32_e32 v128, v128
	v_exp_f32_e32 v127, v126
	v_pk_mul_f32 v[124:125], v[124:125], v[138:139] op_sel_hi:[1,0]
	v_pk_mul_f32 v[114:115], v[114:115], v[138:139] op_sel_hi:[1,0]
	v_add_f32_e32 v126, 1.0, v128
	v_add_f32_e32 v127, 1.0, v127
	v_mul_f32_e32 v128, 0xbfb8aa3b, v124
	v_mul_f32_e32 v129, 0xbfb8aa3b, v125
	v_rcp_f32_e32 v126, v126
	v_rcp_f32_e32 v127, v127
	v_exp_f32_e32 v128, v128
	v_exp_f32_e32 v129, v129
	v_pk_mul_f32 v[122:123], v[122:123], v[126:127]
	v_add_f32_e32 v126, 1.0, v128
	v_add_f32_e32 v127, 1.0, v129
	v_mov_b32_e32 v128, v167
	v_mov_b32_e32 v129, v168
	v_mov_b32_e32 v167, v169
	v_pk_add_f32 v[128:129], v[128:129], v[166:167]
	v_rcp_f32_e32 v126, v126
	v_add_f32_e32 v128, v128, v129
	ds_bpermute_b32 v129, v199, v128
	v_rcp_f32_e32 v127, v127
	v_pk_mul_f32 v[122:123], v[114:115], v[122:123]
	v_pk_mul_f32 v[114:115], v[116:117], v[138:139] op_sel_hi:[1,0]
	v_pk_mul_f32 v[116:117], v[124:125], v[126:127]
	s_waitcnt lgkmcnt(0)
	v_add_f32_e32 v126, v128, v129
	ds_bpermute_b32 v127, v174, v126
	v_pk_mul_f32 v[124:125], v[114:115], v[116:117]
	v_cvt_pk_bf16_f32 v114, v118, v119
	v_cvt_pk_bf16_f32 v115, v120, v121
	v_mad_i64_i32 v[120:121], s[4:5], v208, s68, v[132:133]
	s_waitcnt lgkmcnt(0)
	v_add_f32_e32 v118, v126, v127
	v_fmamk_f32 v118, v118, 0x3a800000, v222
	v_rsq_f32_e32 v118, v118
	v_cvt_pk_bf16_f32 v116, v122, v123
	v_cvt_pk_bf16_f32 v117, v124, v125
	v_lshl_add_u64 v[120:121], v[120:121], 0, v[130:131]
	v_pk_mul_f32 v[110:111], v[110:111], v[118:119] op_sel_hi:[1,0]
	global_store_dwordx4 v[120:121], v[114:117], off
	v_mul_f32_e32 v119, 0xbfb8aa3b, v110
	v_exp_f32_e32 v119, v119
	v_mul_f32_e32 v114, 0xbfb8aa3b, v111
	v_exp_f32_e32 v115, v114
	v_pk_mul_f32 v[112:113], v[112:113], v[118:119] op_sel_hi:[1,0]
	s_nop 0
	v_mul_f32_e32 v116, 0xbfb8aa3b, v112
	v_mul_f32_e32 v117, 0xbfb8aa3b, v113
	v_exp_f32_e32 v116, v116
	v_exp_f32_e32 v117, v117
	v_add_f32_e32 v114, 1.0, v119
	v_add_f32_e32 v115, 1.0, v115
	v_rcp_f32_e32 v114, v114
	v_rcp_f32_e32 v115, v115
	v_add_f32_e32 v116, 1.0, v116
	v_add_f32_e32 v117, 1.0, v117
	v_rcp_f32_e32 v116, v116
	v_rcp_f32_e32 v117, v117
	v_pk_mul_f32 v[98:99], v[98:99], v[118:119] op_sel_hi:[1,0]
	v_pk_mul_f32 v[110:111], v[110:111], v[114:115]
	v_pk_mul_f32 v[100:101], v[100:101], v[118:119] op_sel_hi:[1,0]
	v_pk_mul_f32 v[98:99], v[98:99], v[110:111]
	v_pk_mul_f32 v[110:111], v[112:113], v[116:117]
	v_pk_mul_f32 v[102:103], v[102:103], v[118:119] op_sel_hi:[1,0]
	v_pk_mul_f32 v[100:101], v[100:101], v[110:111]
	v_mul_f32_e32 v112, 0xbfb8aa3b, v102
	v_mul_f32_e32 v110, 0xbfb8aa3b, v103
	v_exp_f32_e32 v112, v112
	v_exp_f32_e32 v111, v110
	v_pk_mul_f32 v[104:105], v[104:105], v[118:119] op_sel_hi:[1,0]
	v_pk_mul_f32 v[94:95], v[94:95], v[118:119] op_sel_hi:[1,0]
	v_add_f32_e32 v110, 1.0, v112
	v_add_f32_e32 v111, 1.0, v111
	v_mul_f32_e32 v112, 0xbfb8aa3b, v104
	v_mul_f32_e32 v113, 0xbfb8aa3b, v105
	v_rcp_f32_e32 v110, v110
	v_rcp_f32_e32 v111, v111
	v_exp_f32_e32 v112, v112
	v_exp_f32_e32 v113, v113
	v_pk_mul_f32 v[102:103], v[102:103], v[110:111]
	v_add_f32_e32 v110, 1.0, v112
	v_add_f32_e32 v111, 1.0, v113
	v_mov_b32_e32 v112, v163
	v_mov_b32_e32 v113, v164
	v_mov_b32_e32 v163, v165
	v_pk_add_f32 v[112:113], v[112:113], v[162:163]
	v_rcp_f32_e32 v110, v110
	v_add_f32_e32 v112, v112, v113
	ds_bpermute_b32 v113, v199, v112
	v_rcp_f32_e32 v111, v111
	v_pk_mul_f32 v[102:103], v[94:95], v[102:103]
	v_pk_mul_f32 v[94:95], v[96:97], v[118:119] op_sel_hi:[1,0]
	v_pk_mul_f32 v[96:97], v[104:105], v[110:111]
	s_waitcnt lgkmcnt(0)
	v_add_f32_e32 v110, v112, v113
	ds_bpermute_b32 v111, v174, v110
	v_pk_mul_f32 v[104:105], v[94:95], v[96:97]
	v_cvt_pk_bf16_f32 v94, v98, v99
	v_cvt_pk_bf16_f32 v95, v100, v101
	v_mad_i64_i32 v[100:101], s[4:5], v206, s68, v[132:133]
	s_waitcnt lgkmcnt(0)
	v_add_f32_e32 v98, v110, v111
	v_fmamk_f32 v98, v98, 0x3a800000, v222
	v_rsq_f32_e32 v98, v98
	v_cvt_pk_bf16_f32 v96, v102, v103
	v_cvt_pk_bf16_f32 v97, v104, v105
	v_lshl_add_u64 v[100:101], v[100:101], 0, v[130:131]
	v_pk_mul_f32 v[90:91], v[90:91], v[98:99] op_sel_hi:[1,0]
	global_store_dwordx4 v[100:101], v[94:97], off
	v_mul_f32_e32 v99, 0xbfb8aa3b, v90
	v_exp_f32_e32 v99, v99
	v_mul_f32_e32 v94, 0xbfb8aa3b, v91
	v_exp_f32_e32 v95, v94
	v_pk_mul_f32 v[92:93], v[92:93], v[98:99] op_sel_hi:[1,0]
	s_nop 0
	v_mul_f32_e32 v96, 0xbfb8aa3b, v92
	v_mul_f32_e32 v97, 0xbfb8aa3b, v93
	v_exp_f32_e32 v96, v96
	v_exp_f32_e32 v97, v97
	v_add_f32_e32 v94, 1.0, v99
	v_add_f32_e32 v95, 1.0, v95
	v_rcp_f32_e32 v94, v94
	v_rcp_f32_e32 v95, v95
	v_add_f32_e32 v96, 1.0, v96
	v_add_f32_e32 v97, 1.0, v97
	v_rcp_f32_e32 v96, v96
	v_rcp_f32_e32 v97, v97
	v_pk_mul_f32 v[78:79], v[78:79], v[98:99] op_sel_hi:[1,0]
	v_pk_mul_f32 v[90:91], v[90:91], v[94:95]
	v_pk_mul_f32 v[82:83], v[82:83], v[98:99] op_sel_hi:[1,0]
	v_pk_mul_f32 v[78:79], v[78:79], v[90:91]
	v_pk_mul_f32 v[90:91], v[92:93], v[96:97]
	v_mul_f32_e32 v92, 0xbfb8aa3b, v82
	v_exp_f32_e32 v92, v92
	v_pk_mul_f32 v[80:81], v[80:81], v[98:99] op_sel_hi:[1,0]
	v_pk_mul_f32 v[84:85], v[84:85], v[98:99] op_sel_hi:[1,0]
	v_pk_mul_f32 v[80:81], v[80:81], v[90:91]
	v_mul_f32_e32 v90, 0xbfb8aa3b, v83
	v_exp_f32_e32 v91, v90
	v_add_f32_e32 v90, 1.0, v92
	v_mul_f32_e32 v92, 0xbfb8aa3b, v84
	v_mul_f32_e32 v93, 0xbfb8aa3b, v85
	v_exp_f32_e32 v92, v92
	v_exp_f32_e32 v93, v93
	v_add_f32_e32 v91, 1.0, v91
	v_rcp_f32_e32 v90, v90
	v_rcp_f32_e32 v91, v91
	v_add_f32_e32 v92, 1.0, v92
	v_add_f32_e32 v93, 1.0, v93
	v_rcp_f32_e32 v92, v92
	v_rcp_f32_e32 v93, v93
	v_pk_mul_f32 v[74:75], v[74:75], v[98:99] op_sel_hi:[1,0]
	v_pk_mul_f32 v[82:83], v[82:83], v[90:91]
	s_nop 0
	v_pk_mul_f32 v[82:83], v[74:75], v[82:83]
	v_pk_mul_f32 v[74:75], v[76:77], v[98:99] op_sel_hi:[1,0]
	v_pk_mul_f32 v[76:77], v[84:85], v[92:93]
	s_nop 0
	v_pk_mul_f32 v[84:85], v[74:75], v[76:77]
	v_cvt_pk_bf16_f32 v74, v78, v79
	v_mad_i64_i32 v[78:79], s[4:5], v204, s68, v[132:133]
	v_cvt_pk_bf16_f32 v75, v80, v81
	v_cvt_pk_bf16_f32 v76, v82, v83
	v_cvt_pk_bf16_f32 v77, v84, v85
	v_lshl_add_u64 v[78:79], v[78:79], 0, v[130:131]
	global_store_dwordx4 v[78:79], v[74:77], off
	s_andn2_b64 vcc, exec, s[6:7]
	s_cbranch_vccnz .LBB0_1030
	s_cmpk_gt_i32 s2, 0xf7
	s_cselect_b64 s[46:47], -1, 0
	s_cmpk_gt_u32 s2, 0x4ef
	s_cselect_b64 s[6:7], -1, 0
	s_cmpk_lt_u32 s2, 0x14e8
	s_cselect_b64 s[4:5], -1, 0
	s_and_b64 s[4:5], s[4:5], exec
	s_movk_i32 s11, 0x80
	s_mov_b64 s[44:45], 0x20a0000
	v_cndmask_b32_e64 v74, 0, 1, s[6:7]
	s_cselect_b32 s10, s69, 0x54dc000
	s_cselect_b32 s0, s11, 0x100
	s_cselect_b32 s3, 0x800, 30
	s_cselect_b32 s4, 0x7fc, 26
	s_cselect_b32 s5, s67, 0xffffeb18
	s_cmpk_lt_i32 s2, 0xf8
	s_mov_b32 s22, 0
	s_movk_i32 s39, 0x7c
	v_cmp_ne_u32_e64 s[6:7], 1, v74
	s_mov_b64 s[8:9], 0x20a0000
	s_movk_i32 s45, 0x80
	s_movk_i32 s73, 0x80
	s_movk_i32 s75, 0x7c
	s_mov_b32 s74, 0
	s_cbranch_scc1 .LBB0_1017
	s_and_b64 vcc, exec, s[6:7]
	s_cbranch_vccnz .LBB0_1016
	s_mov_b32 s74, s5
	s_mov_b32 s75, s4
	s_mov_b32 s73, s3
	s_mov_b32 s45, s0
	s_mov_b64 s[8:9], s[10:11]
	s_branch .LBB0_1017

.LBB0_1017:
	s_mul_i32 s9, s75, s45
	v_cvt_f32_u32_e32 v74, s9
	s_add_i32 s74, s74, s2
	s_lshl_b32 s74, s74, 11
	s_sub_i32 s75, 0, s9
	v_rcp_iflag_f32_e32 v74, v74
	s_ashr_i32 s76, s74, 31
	s_abs_i32 s77, s74
	v_add_u32_e32 v76, s74, v215
	v_mul_f32_e32 v74, 0x4f7ffffe, v74
	v_cvt_u32_f32_e32 v74, v74
	v_mov_b32_e32 v75, s9
	v_readfirstlane_b32 s74, v74
	s_mul_i32 s75, s75, s74
	s_mul_hi_u32 s75, s74, s75
	s_add_i32 s74, s74, s75
	s_mul_hi_u32 s74, s77, s74
	s_mul_i32 s75, s74, s9
	s_sub_i32 s75, s77, s75
	s_add_i32 s78, s74, 1
	s_sub_i32 s77, s75, s9
	s_cmp_ge_u32 s75, s9
	s_cselect_b32 s74, s78, s74
	s_cselect_b32 s75, s77, s75
	s_add_i32 s77, s74, 1
	s_cmp_ge_u32 s75, s9
	s_cselect_b32 s74, s77, s74
	s_xor_b32 s74, s74, s76
	s_sub_i32 s74, s74, s76
	s_mul_i32 s75, s74, s9
	v_subrev_u32_e32 v74, s75, v76
	v_cmp_le_i32_e32 vcc, s9, v74
	s_mul_i32 s9, s73, s45
	s_lshl_b32 s8, s8, 2
	v_cndmask_b32_e32 v75, 0, v75, vcc
	v_sub_u32_e32 v74, v74, v75
	v_mov_b32_e32 v75, s74
	v_addc_co_u32_e32 v75, vcc, 0, v75, vcc
	v_mad_u64_u32 v[74:75], s[74:75], s9, v75, v[74:75]
	s_add_u32 s8, s20, s8
	v_mov_b32_e32 v75, v185
	s_addc_u32 s9, s21, 0
	v_lshl_add_u64 v[74:75], v[74:75], 4, s[8:9]
	s_waitcnt vmcnt(4)
	global_store_dwordx4 v[74:75], v[146:149], off nt
	v_cndmask_b32_e64 v74, 0, 1, s[46:47]
	v_cmp_ne_u32_e64 s[8:9], 1, v74
	s_andn2_b64 vcc, exec, s[46:47]
	s_movk_i32 s46, 0x80
	s_cbranch_vccnz .LBB0_1021
	s_and_b64 vcc, exec, s[6:7]
	s_cbranch_vccnz .LBB0_1020
	s_mov_b32 s11, s0
	s_mov_b32 s22, s5
	s_mov_b32 s39, s4
	s_mov_b32 s46, s3
	s_mov_b64 s[44:45], s[10:11]
	s_branch .LBB0_1021

	.amdhsa_kernel _Z10fwd_kernel6Params
		.amdhsa_group_segment_fixed_size 0
		.amdhsa_private_segment_fixed_size 0
		.amdhsa_kernarg_size 440
		.amdhsa_user_sgpr_count 2
		.amdhsa_user_sgpr_dispatch_ptr 0
		.amdhsa_user_sgpr_queue_ptr 0
		.amdhsa_user_sgpr_kernarg_segment_ptr 1
		.amdhsa_user_sgpr_dispatch_id 0
		.amdhsa_user_sgpr_kernarg_preload_length 0
		.amdhsa_user_sgpr_kernarg_preload_offset 0
		.amdhsa_user_sgpr_private_segment_size 0
		.amdhsa_uses_dynamic_stack 0
		.amdhsa_enable_private_segment 0
		.amdhsa_system_sgpr_workgroup_id_x 1
		.amdhsa_system_sgpr_workgroup_id_y 0
		.amdhsa_system_sgpr_workgroup_id_z 0
		.amdhsa_system_sgpr_workgroup_info 0
		.amdhsa_system_vgpr_workitem_id 0
		.amdhsa_next_free_vgpr 256
		.amdhsa_next_free_sgpr 102
		.amdhsa_accum_offset 256
		.amdhsa_reserve_vcc 1
		.amdhsa_float_round_mode_32 0
		.amdhsa_float_round_mode_16_64 0
		.amdhsa_float_denorm_mode_32 3
		.amdhsa_float_denorm_mode_16_64 3
		.amdhsa_dx10_clamp 1
		.amdhsa_ieee_mode 1
		.amdhsa_fp16_overflow 0
		.amdhsa_tg_split 0
		.amdhsa_exception_fp_ieee_invalid_op 0
		.amdhsa_exception_fp_denorm_src 0
		.amdhsa_exception_fp_ieee_div_zero 0
		.amdhsa_exception_fp_ieee_overflow 0
		.amdhsa_exception_fp_ieee_underflow 0
		.amdhsa_exception_fp_ieee_inexact 0
		.amdhsa_exception_int_div_zero 0
	.end_amdhsa_kernel

amdhsa.kernels:
  - .agpr_count:     0
    .args:
      - .offset:         0
        .size:           184
        .value_kind:     by_value
      - .offset:         184
        .size:           4
        .value_kind:     hidden_block_count_x
      - .offset:         188
        .size:           4
        .value_kind:     hidden_block_count_y
      - .offset:         192
        .size:           4
        .value_kind:     hidden_block_count_z
      - .offset:         196
        .size:           2
        .value_kind:     hidden_group_size_x
      - .offset:         198
        .size:           2
        .value_kind:     hidden_group_size_y
      - .offset:         200
        .size:           2
        .value_kind:     hidden_group_size_z
      - .offset:         202
        .size:           2
        .value_kind:     hidden_remainder_x
      - .offset:         204
        .size:           2
        .value_kind:     hidden_remainder_y
      - .offset:         206
        .size:           2
        .value_kind:     hidden_remainder_z
      - .offset:         224
        .size:           8
        .value_kind:     hidden_global_offset_x
      - .offset:         232
        .size:           8
        .value_kind:     hidden_global_offset_y
      - .offset:         240
        .size:           8
        .value_kind:     hidden_global_offset_z
      - .offset:         248
        .size:           2
        .value_kind:     hidden_grid_dims
      - .offset:         304
        .size:           4
        .value_kind:     hidden_dynamic_lds_size
    .group_segment_fixed_size: 0
    .kernarg_segment_align: 8
    .kernarg_segment_size: 440
    .language:       OpenCL C
    .language_version:
      - 2
      - 0
    .max_flat_workgroup_size: 512
    .name:           _Z10fwd_kernel6Params
    .private_segment_fixed_size: 0
    .sgpr_count:     108
    .sgpr_spill_count: 29
    .symbol:         _Z10fwd_kernel6Params.kd
    .uniform_work_group_size: 1
    .uses_dynamic_stack: false
    .vgpr_count:     256
    .vgpr_spill_count: 0
    .wavefront_size: 64
